# LN gamma/beta hoisted out of the per-row chains in D and F; out-proj epilogue issues its 16 residual loads up front; E2 epilogue loads its 4 gates up front
# speedup vs baseline: 1.0861x; 1.0248x over previous
; __device__ void phaseC(const Params& p, char* smem, int which) {
;     ...
;     auto epi = [&](f32x4 (&acc)[4][4], int mb, int nb) {
; #pragma unroll
;       for (int mi = 0; mi < 4; mi++)
; #pragma unroll
;         for (int ni = 0; ni < 4; ni++) {
;           const int m = m0 + mb + mi * 16;
;           const size_t idx = (size_t)m * DM + n0 + nb + ni * 16;
;           float4 xv = *(const float4*)&p.x[idx];
;           f32x4 v = acc[mi][ni];
;           float* zp = (half == 0) ? (p.LF + ((size_t)((m >> 11) * 1024 + (m & 1023))) * DM + n0 + nb + ni * 16) : (p.Z + idx);
;           *(float4*)zp = make_float4(ALPHA * xv.x + v[0], ALPHA * xv.y + v[1], ALPHA * xv.z + v[2], ALPHA * xv.w + v[3]);
;         }
;     };
.LBB0_892:
	v_add_u32_e32 v76, v99, v126
	v_ashrrev_i32_e32 v77, 31, v76
	v_lshlrev_b64 v[78:79], 12, v[76:77]
	v_lshl_add_u64 v[52:53], v[122:123], 0, v[78:79]
	global_load_dwordx4 v[150:153], v[52:53], off
	global_load_dwordx4 v[154:157], v[52:53], off offset:64
	global_load_dwordx4 v[172:175], v[52:53], off offset:128
	global_load_dwordx4 v[176:179], v[52:53], off offset:192
	v_ashrrev_i32_e32 v77, 1, v76
	v_and_b32_e32 v76, 0x3cf, v76
	v_and_or_b32 v76, v77, s30, v76
	v_ashrrev_i32_e32 v77, 31, v76
	v_lshlrev_b64 v[76:77], 12, v[76:77]
	v_lshl_add_u64 v[68:69], v[112:113], 0, v[76:77]
	v_add_u32_e32 v76, v99, v166
	v_ashrrev_i32_e32 v77, 31, v76
	v_lshlrev_b64 v[78:79], 12, v[76:77]
	v_lshl_add_u64 v[54:55], v[122:123], 0, v[78:79]
	global_load_dwordx4 v[180:183], v[54:55], off
	global_load_dwordx4 v[184:187], v[54:55], off offset:64
	global_load_dwordx4 v[188:191], v[54:55], off offset:128
	global_load_dwordx4 v[192:195], v[54:55], off offset:192
	v_ashrrev_i32_e32 v77, 1, v76
	v_and_b32_e32 v76, 0x3df, v76
	v_and_or_b32 v76, v77, s30, v76
	v_ashrrev_i32_e32 v77, 31, v76
	v_lshlrev_b64 v[76:77], 12, v[76:77]
	v_lshl_add_u64 v[70:71], v[112:113], 0, v[76:77]
	v_add_u32_e32 v76, v99, v167
	v_ashrrev_i32_e32 v77, 31, v76
	v_lshlrev_b64 v[78:79], 12, v[76:77]
	v_lshl_add_u64 v[56:57], v[122:123], 0, v[78:79]
	global_load_dwordx4 v[196:199], v[56:57], off
	global_load_dwordx4 v[200:203], v[56:57], off offset:64
	global_load_dwordx4 v[204:207], v[56:57], off offset:128
	global_load_dwordx4 v[208:211], v[56:57], off offset:192
	v_ashrrev_i32_e32 v77, 1, v76
	v_and_b32_e32 v76, 0x3ef, v76
	v_and_or_b32 v76, v77, s30, v76
	v_ashrrev_i32_e32 v77, 31, v76
	v_lshlrev_b64 v[76:77], 12, v[76:77]
	v_lshl_add_u64 v[72:73], v[112:113], 0, v[76:77]
	v_add_u32_e32 v76, v99, v168
	v_ashrrev_i32_e32 v77, 31, v76
	v_lshlrev_b64 v[78:79], 12, v[76:77]
	v_lshl_add_u64 v[58:59], v[122:123], 0, v[78:79]
	global_load_dwordx4 v[212:215], v[58:59], off
	global_load_dwordx4 v[216:219], v[58:59], off offset:64
	global_load_dwordx4 v[220:223], v[58:59], off offset:128
	global_load_dwordx4 v[224:227], v[58:59], off offset:192
	v_ashrrev_i32_e32 v77, 1, v76
	v_bfi_b32 v76, s30, v77, v76
	v_ashrrev_i32_e32 v77, 31, v76
	v_lshlrev_b64 v[76:77], 12, v[76:77]
	v_lshl_add_u64 v[74:75], v[112:113], 0, v[76:77]
	s_waitcnt vmcnt(15)
	v_pk_fma_f32 v[60:61], v[150:151], s[0:1], v[60:61] op_sel_hi:[1,0,1]
	v_pk_fma_f32 v[62:63], v[152:153], s[0:1], v[62:63] op_sel_hi:[1,0,1]
	global_store_dwordx4 v[68:69], v[60:63], off
	s_waitcnt vmcnt(15)
	v_pk_fma_f32 v[84:85], v[154:155], s[0:1], v[84:85] op_sel_hi:[1,0,1]
	v_pk_fma_f32 v[86:87], v[156:157], s[0:1], v[86:87] op_sel_hi:[1,0,1]
	global_store_dwordx4 v[68:69], v[84:87], off offset:64
	s_waitcnt vmcnt(15)
	v_pk_fma_f32 v[64:65], v[172:173], s[0:1], v[64:65] op_sel_hi:[1,0,1]
	v_pk_fma_f32 v[66:67], v[174:175], s[0:1], v[66:67] op_sel_hi:[1,0,1]
	global_store_dwordx4 v[68:69], v[64:67], off offset:128
	s_waitcnt vmcnt(15)
	v_pk_fma_f32 v[48:49], v[176:177], s[0:1], v[48:49] op_sel_hi:[1,0,1]
	v_pk_fma_f32 v[50:51], v[178:179], s[0:1], v[50:51] op_sel_hi:[1,0,1]
	global_store_dwordx4 v[68:69], v[48:51], off offset:192
	s_waitcnt vmcnt(15)
	v_pk_fma_f32 v[44:45], v[180:181], s[0:1], v[44:45] op_sel_hi:[1,0,1]
	v_pk_fma_f32 v[46:47], v[182:183], s[0:1], v[46:47] op_sel_hi:[1,0,1]
	global_store_dwordx4 v[70:71], v[44:47], off
	s_waitcnt vmcnt(15)
	v_pk_fma_f32 v[40:41], v[184:185], s[0:1], v[40:41] op_sel_hi:[1,0,1]
	v_pk_fma_f32 v[42:43], v[186:187], s[0:1], v[42:43] op_sel_hi:[1,0,1]
	global_store_dwordx4 v[70:71], v[40:43], off offset:64
	s_waitcnt vmcnt(15)
	v_pk_fma_f32 v[36:37], v[188:189], s[0:1], v[36:37] op_sel_hi:[1,0,1]
	v_pk_fma_f32 v[38:39], v[190:191], s[0:1], v[38:39] op_sel_hi:[1,0,1]
	global_store_dwordx4 v[70:71], v[36:39], off offset:128
	s_waitcnt vmcnt(15)
	v_pk_fma_f32 v[32:33], v[192:193], s[0:1], v[32:33] op_sel_hi:[1,0,1]
	v_pk_fma_f32 v[34:35], v[194:195], s[0:1], v[34:35] op_sel_hi:[1,0,1]
	global_store_dwordx4 v[70:71], v[32:35], off offset:192
	s_waitcnt vmcnt(15)
	v_pk_fma_f32 v[28:29], v[196:197], s[0:1], v[28:29] op_sel_hi:[1,0,1]
	v_pk_fma_f32 v[30:31], v[198:199], s[0:1], v[30:31] op_sel_hi:[1,0,1]
	global_store_dwordx4 v[72:73], v[28:31], off
	s_waitcnt vmcnt(15)
	v_pk_fma_f32 v[24:25], v[200:201], s[0:1], v[24:25] op_sel_hi:[1,0,1]
	v_pk_fma_f32 v[26:27], v[202:203], s[0:1], v[26:27] op_sel_hi:[1,0,1]
	global_store_dwordx4 v[72:73], v[24:27], off offset:64
	s_waitcnt vmcnt(15)
	v_pk_fma_f32 v[20:21], v[204:205], s[0:1], v[20:21] op_sel_hi:[1,0,1]
	v_pk_fma_f32 v[22:23], v[206:207], s[0:1], v[22:23] op_sel_hi:[1,0,1]
	global_store_dwordx4 v[72:73], v[20:23], off offset:128
	s_waitcnt vmcnt(15)
	v_pk_fma_f32 v[16:17], v[208:209], s[0:1], v[16:17] op_sel_hi:[1,0,1]
	v_pk_fma_f32 v[18:19], v[210:211], s[0:1], v[18:19] op_sel_hi:[1,0,1]
	global_store_dwordx4 v[72:73], v[16:19], off offset:192
	s_waitcnt vmcnt(15)
	v_pk_fma_f32 v[12:13], v[212:213], s[0:1], v[12:13] op_sel_hi:[1,0,1]
	v_pk_fma_f32 v[14:15], v[214:215], s[0:1], v[14:15] op_sel_hi:[1,0,1]
	global_store_dwordx4 v[74:75], v[12:15], off
	s_waitcnt vmcnt(15)
	v_pk_fma_f32 v[8:9], v[216:217], s[0:1], v[8:9] op_sel_hi:[1,0,1]
	v_pk_fma_f32 v[10:11], v[218:219], s[0:1], v[10:11] op_sel_hi:[1,0,1]
	global_store_dwordx4 v[74:75], v[8:11], off offset:64
	s_waitcnt vmcnt(15)
	v_pk_fma_f32 v[4:5], v[220:221], s[0:1], v[4:5] op_sel_hi:[1,0,1]
	v_pk_fma_f32 v[6:7], v[222:223], s[0:1], v[6:7] op_sel_hi:[1,0,1]
	global_store_dwordx4 v[74:75], v[4:7], off offset:128
	s_waitcnt vmcnt(15)
	v_pk_fma_f32 v[0:1], v[224:225], s[0:1], v[0:1] op_sel_hi:[1,0,1]
	v_pk_fma_f32 v[2:3], v[226:227], s[0:1], v[2:3] op_sel_hi:[1,0,1]
	global_store_dwordx4 v[74:75], v[0:3], off offset:192
	s_xor_b64 s[20:21], exec, -1

; __device__ void phaseC(const Params& p, char* smem, int which) {
;     ...
;   xcd_queue_run(p.bar + QW_BASE + 512 + 32 * half, half ? 72 : 56, smem + 2 * GEMM_SMEM + 800, [&](int j, int q) {
;     const int mt = half ? ((q / 9) * 16 + 7 + q % 9) : ((q / 7) * 16 + q % 7), nt = j;
;     const int m0 = mt * 128, n0 = nt * 128;
;     auto rowf = [&](int r) { return (const void*)(p.O + (size_t)(m0 + r) * DM); };
;     auto colf = [&](int c) { return (const void*)(p.WoutT + (size_t)(n0 + c) * DM); };
;     auto epi = [&](f32x4 (&acc)[4][4], int mb, int nb) {
; #pragma unroll
;       for (int mi = 0; mi < 4; mi++)
; #pragma unroll
;         for (int ni = 0; ni < 4; ni++) {
;           const int m = m0 + mb + mi * 16;
;           const size_t idx = (size_t)m * DM + n0 + nb + ni * 16;
;           float4 xv = *(const float4*)&p.x[idx];
;           f32x4 v = acc[mi][ni];
;           float* zp = (half == 0) ? (p.LF + ((size_t)((m >> 11) * 1024 + (m & 1023))) * DM + n0 + nb + ni * 16) : (p.Z + idx);
;           *(float4*)zp = make_float4(ALPHA * xv.x + v[0], ALPHA * xv.y + v[1], ALPHA * xv.z + v[2], ALPHA * xv.w + v[3]);
;         }
;     };
;     gemm_tile<true, true>(smem, DM, rowf, colf, DM, epi);
.LBB0_1027:
	s_and_b32 s8, s42, 7
	v_lshl_or_b32 v96, s8, 18, v138
	s_add_i32 s8, s43, s41
	s_and_b32 s8, s8, 7
	s_lshl_b32 s18, s8, 8
	s_add_u32 s18, s38, s18
	s_addc_u32 s19, s39, 0
	s_lshl_b32 s20, s8, 7
	v_or_b32_e32 v0, s20, v160
	v_lshl_add_u64 v[106:107], s[72:73], 0, v[96:97]
	v_lshlrev_b32_e32 v96, 11, v0
	v_or_b32_e32 v108, s20, v130
	s_lshl_b32 s8, s8, 9
	v_lshl_add_u64 v[112:113], v[104:105], 0, v[96:97]
	s_mov_b64 s[20:21], 0x10000
	v_mov_b32_e32 v109, v99
	v_lshl_add_u64 v[110:111], v[100:101], 0, s[8:9]
	v_lshl_add_u64 v[114:115], v[112:113], 0, s[20:21]
	v_lshl_add_u64 v[116:117], v[112:113], 0, s[10:11]
	v_lshl_add_u64 v[118:119], v[112:113], 0, s[12:13]
	s_mov_b64 s[20:21], 0
	s_branch .LBB0_1030
.LBB0_1029:
	s_or_b64 exec, exec, s[22:23]
	s_and_b64 s[22:23], exec, s[24:25]
	s_or_b64 s[20:21], s[22:23], s[20:21]
	s_andn2_b64 exec, exec, s[20:21]
	s_cbranch_execz .LBB0_1026

; __device__ void phaseC(const Params& p, char* smem, int which) {
;     ...
;     auto epi = [&](f32x4 (&acc)[4][4], int mb, int nb) {
; #pragma unroll
;       for (int mi = 0; mi < 4; mi++)
; #pragma unroll
;         for (int ni = 0; ni < 4; ni++) {
;           const int m = m0 + mb + mi * 16;
;           const size_t idx = (size_t)m * DM + n0 + nb + ni * 16;
;           float4 xv = *(const float4*)&p.x[idx];
;           f32x4 v = acc[mi][ni];
;           float* zp = (half == 0) ? (p.LF + ((size_t)((m >> 11) * 1024 + (m & 1023))) * DM + n0 + nb + ni * 16) : (p.Z + idx);
;           *(float4*)zp = make_float4(ALPHA * xv.x + v[0], ALPHA * xv.y + v[1], ALPHA * xv.z + v[2], ALPHA * xv.w + v[3]);
;         }
;     };
.LBB0_1045:
	v_add_u32_e32 v80, v96, v126
	v_ashrrev_i32_e32 v81, 31, v80
	v_lshlrev_b64 v[82:83], 10, v[80:81]
	v_lshl_add_u64 v[82:83], v[82:83], 0, v[108:109]
	v_lshl_add_u64 v[64:65], v[82:83], 2, s[52:53]
	global_load_dwordx4 v[146:149], v[64:65], off
	global_load_dwordx4 v[150:153], v[64:65], off offset:64
	global_load_dwordx4 v[154:157], v[64:65], off offset:128
	global_load_dwordx4 v[172:175], v[64:65], off offset:192
	v_lshl_add_u64 v[84:85], v[82:83], 2, s[94:95]
	v_ashrrev_i32_e32 v81, 1, v80
	v_and_b32_e32 v80, 0x3cf, v80
	v_and_or_b32 v80, v81, s36, v80
	v_ashrrev_i32_e32 v81, 31, v80
	v_lshlrev_b64 v[80:81], 12, v[80:81]
	v_lshl_add_u64 v[86:87], v[110:111], 0, v[80:81]
	v_cndmask_b32_e64 v72, v86, v84, s[16:17]
	v_cndmask_b32_e64 v73, v87, v85, s[16:17]
	v_add_u32_e32 v80, v96, v166
	v_ashrrev_i32_e32 v81, 31, v80
	v_lshlrev_b64 v[82:83], 10, v[80:81]
	v_lshl_add_u64 v[82:83], v[82:83], 0, v[108:109]
	v_lshl_add_u64 v[66:67], v[82:83], 2, s[52:53]
	global_load_dwordx4 v[176:179], v[66:67], off
	global_load_dwordx4 v[180:183], v[66:67], off offset:64
	global_load_dwordx4 v[184:187], v[66:67], off offset:128
	global_load_dwordx4 v[188:191], v[66:67], off offset:192
	v_lshl_add_u64 v[84:85], v[82:83], 2, s[94:95]
	v_ashrrev_i32_e32 v81, 1, v80
	v_and_b32_e32 v80, 0x3df, v80
	v_and_or_b32 v80, v81, s36, v80
	v_ashrrev_i32_e32 v81, 31, v80
	v_lshlrev_b64 v[80:81], 12, v[80:81]
	v_lshl_add_u64 v[86:87], v[110:111], 0, v[80:81]
	v_cndmask_b32_e64 v74, v86, v84, s[16:17]
	v_cndmask_b32_e64 v75, v87, v85, s[16:17]
	v_add_u32_e32 v80, v96, v167
	v_ashrrev_i32_e32 v81, 31, v80
	v_lshlrev_b64 v[82:83], 10, v[80:81]
	v_lshl_add_u64 v[82:83], v[82:83], 0, v[108:109]
	v_lshl_add_u64 v[68:69], v[82:83], 2, s[52:53]
	global_load_dwordx4 v[192:195], v[68:69], off
	global_load_dwordx4 v[196:199], v[68:69], off offset:64
	global_load_dwordx4 v[200:203], v[68:69], off offset:128
	global_load_dwordx4 v[204:207], v[68:69], off offset:192
	v_lshl_add_u64 v[84:85], v[82:83], 2, s[94:95]
	v_ashrrev_i32_e32 v81, 1, v80
	v_and_b32_e32 v80, 0x3ef, v80
	v_and_or_b32 v80, v81, s36, v80
	v_ashrrev_i32_e32 v81, 31, v80
	v_lshlrev_b64 v[80:81], 12, v[80:81]
	v_lshl_add_u64 v[86:87], v[110:111], 0, v[80:81]
	v_cndmask_b32_e64 v76, v86, v84, s[16:17]
	v_cndmask_b32_e64 v77, v87, v85, s[16:17]
	v_add_u32_e32 v80, v96, v168
	v_ashrrev_i32_e32 v81, 31, v80
	v_lshlrev_b64 v[82:83], 10, v[80:81]
	v_lshl_add_u64 v[82:83], v[82:83], 0, v[108:109]
	v_lshl_add_u64 v[70:71], v[82:83], 2, s[52:53]
	global_load_dwordx4 v[208:211], v[70:71], off
	global_load_dwordx4 v[212:215], v[70:71], off offset:64
	global_load_dwordx4 v[216:219], v[70:71], off offset:128
	global_load_dwordx4 v[220:223], v[70:71], off offset:192
	v_lshl_add_u64 v[84:85], v[82:83], 2, s[94:95]
	v_ashrrev_i32_e32 v81, 1, v80
	v_bfi_b32 v80, s36, v81, v80
	v_ashrrev_i32_e32 v81, 31, v80
	v_lshlrev_b64 v[80:81], 12, v[80:81]
	v_lshl_add_u64 v[86:87], v[110:111], 0, v[80:81]
	v_cndmask_b32_e64 v78, v86, v84, s[16:17]
	v_cndmask_b32_e64 v79, v87, v85, s[16:17]
	s_waitcnt vmcnt(15)
	v_pk_fma_f32 v[60:61], v[146:147], s[0:1], v[60:61] op_sel_hi:[1,0,1]
	v_pk_fma_f32 v[62:63], v[148:149], s[0:1], v[62:63] op_sel_hi:[1,0,1]
	global_store_dwordx4 v[72:73], v[60:63], off
	s_waitcnt vmcnt(15)
	v_pk_fma_f32 v[56:57], v[150:151], s[0:1], v[56:57] op_sel_hi:[1,0,1]
	v_pk_fma_f32 v[58:59], v[152:153], s[0:1], v[58:59] op_sel_hi:[1,0,1]
	global_store_dwordx4 v[72:73], v[56:59], off offset:64
	s_waitcnt vmcnt(15)
	v_pk_fma_f32 v[52:53], v[154:155], s[0:1], v[52:53] op_sel_hi:[1,0,1]
	v_pk_fma_f32 v[54:55], v[156:157], s[0:1], v[54:55] op_sel_hi:[1,0,1]
	global_store_dwordx4 v[72:73], v[52:55], off offset:128
	s_waitcnt vmcnt(15)
	v_pk_fma_f32 v[48:49], v[172:173], s[0:1], v[48:49] op_sel_hi:[1,0,1]
	v_pk_fma_f32 v[50:51], v[174:175], s[0:1], v[50:51] op_sel_hi:[1,0,1]
	global_store_dwordx4 v[72:73], v[48:51], off offset:192
	s_waitcnt vmcnt(15)
	v_pk_fma_f32 v[44:45], v[176:177], s[0:1], v[44:45] op_sel_hi:[1,0,1]
	v_pk_fma_f32 v[46:47], v[178:179], s[0:1], v[46:47] op_sel_hi:[1,0,1]
	global_store_dwordx4 v[74:75], v[44:47], off
	s_waitcnt vmcnt(15)
	v_pk_fma_f32 v[40:41], v[180:181], s[0:1], v[40:41] op_sel_hi:[1,0,1]
	v_pk_fma_f32 v[42:43], v[182:183], s[0:1], v[42:43] op_sel_hi:[1,0,1]
	global_store_dwordx4 v[74:75], v[40:43], off offset:64
	s_waitcnt vmcnt(15)
	v_pk_fma_f32 v[36:37], v[184:185], s[0:1], v[36:37] op_sel_hi:[1,0,1]
	v_pk_fma_f32 v[38:39], v[186:187], s[0:1], v[38:39] op_sel_hi:[1,0,1]
	global_store_dwordx4 v[74:75], v[36:39], off offset:128
	s_waitcnt vmcnt(15)
	v_pk_fma_f32 v[32:33], v[188:189], s[0:1], v[32:33] op_sel_hi:[1,0,1]
	v_pk_fma_f32 v[34:35], v[190:191], s[0:1], v[34:35] op_sel_hi:[1,0,1]
	global_store_dwordx4 v[74:75], v[32:35], off offset:192
	s_waitcnt vmcnt(15)
	v_pk_fma_f32 v[28:29], v[192:193], s[0:1], v[28:29] op_sel_hi:[1,0,1]
	v_pk_fma_f32 v[30:31], v[194:195], s[0:1], v[30:31] op_sel_hi:[1,0,1]
	global_store_dwordx4 v[76:77], v[28:31], off
	s_waitcnt vmcnt(15)
	v_pk_fma_f32 v[24:25], v[196:197], s[0:1], v[24:25] op_sel_hi:[1,0,1]
	v_pk_fma_f32 v[26:27], v[198:199], s[0:1], v[26:27] op_sel_hi:[1,0,1]
	global_store_dwordx4 v[76:77], v[24:27], off offset:64
	s_waitcnt vmcnt(15)
	v_pk_fma_f32 v[20:21], v[200:201], s[0:1], v[20:21] op_sel_hi:[1,0,1]
	v_pk_fma_f32 v[22:23], v[202:203], s[0:1], v[22:23] op_sel_hi:[1,0,1]
	global_store_dwordx4 v[76:77], v[20:23], off offset:128
	s_waitcnt vmcnt(15)
	v_pk_fma_f32 v[16:17], v[204:205], s[0:1], v[16:17] op_sel_hi:[1,0,1]
	v_pk_fma_f32 v[18:19], v[206:207], s[0:1], v[18:19] op_sel_hi:[1,0,1]
	global_store_dwordx4 v[76:77], v[16:19], off offset:192
	s_waitcnt vmcnt(15)
	v_pk_fma_f32 v[12:13], v[208:209], s[0:1], v[12:13] op_sel_hi:[1,0,1]
	v_pk_fma_f32 v[14:15], v[210:211], s[0:1], v[14:15] op_sel_hi:[1,0,1]
	global_store_dwordx4 v[78:79], v[12:15], off
	s_waitcnt vmcnt(15)
	v_pk_fma_f32 v[8:9], v[212:213], s[0:1], v[8:9] op_sel_hi:[1,0,1]
	v_pk_fma_f32 v[10:11], v[214:215], s[0:1], v[10:11] op_sel_hi:[1,0,1]
	global_store_dwordx4 v[78:79], v[8:11], off offset:64
	s_waitcnt vmcnt(15)
	v_pk_fma_f32 v[4:5], v[216:217], s[0:1], v[4:5] op_sel_hi:[1,0,1]
	v_pk_fma_f32 v[6:7], v[218:219], s[0:1], v[6:7] op_sel_hi:[1,0,1]
	global_store_dwordx4 v[78:79], v[4:7], off offset:128
	s_waitcnt vmcnt(15)
	v_pk_fma_f32 v[0:1], v[220:221], s[0:1], v[0:1] op_sel_hi:[1,0,1]
	v_pk_fma_f32 v[2:3], v[222:223], s[0:1], v[2:3] op_sel_hi:[1,0,1]
	global_store_dwordx4 v[78:79], v[0:3], off offset:192
	s_xor_b64 s[24:25], exec, -1
	s_branch .LBB0_1029

; __device__ void phaseD(const Params& p, char* smem) {
;   float* part = (float*)smem;
;   float* logits = part + 4 * 16 * 80;
;   float* stats = logits + 16 * 72;
;   const int tid = threadIdx.x, lane = tid & 63, w = tid >> 6, l15 = lane & 15, kg = lane >> 4;
;   for (int g = blockIdx.x; g < NTOK / 16; g += gridDim.x) {
;     const int row0 = g * 16;
;     {
;       float4 v[4][4];
; #pragma unroll
;       for (int i = 0; i < 4; i++)
; #pragma unroll
;         for (int j = 0; j < 4; j++) {
;           const int row = row0 + w * 4 + i;
;           const float* zr = ((row & 2047) >= 896) ? (p.Z + (size_t)row * DM) : (p.LF + ((size_t)((row >> 11) * 1024 + (row & 1023))) * DM);
;           v[i][j] = *(const float4*)&zr[lane * 4 + 256 * j];
;         }
; #pragma unroll
;       for (int i = 0; i < 4; i++) {
;         const int row = row0 + w * 4 + i;
;         float s = 0.f;
; #pragma unroll
;         for (int j = 0; j < 4; j++) s += v[i][j].x + v[i][j].y + v[i][j].z + v[i][j].w;
;         const float mu = wave_sum(s) * (1.f / 1024.f);
;         float q = 0.f;
; #pragma unroll
;         for (int j = 0; j < 4; j++) {
;           v[i][j].x -= mu; v[i][j].y -= mu; v[i][j].z -= mu; v[i][j].w -= mu;
;           q += v[i][j].x * v[i][j].x + v[i][j].y * v[i][j].y + v[i][j].z * v[i][j].z + v[i][j].w * v[i][j].w;
;         }
;         const float rstd = rsqrtf(wave_sum(q) * (1.f / 1024.f) + LN_EPS);
;         if (lane == 0) { stats[(w * 4 + i) * 2] = mu; stats[(w * 4 + i) * 2 + 1] = rstd; }
; #pragma unroll
;         for (int j = 0; j < 4; j++) {
;           const float4 gg = *(const float4*)&p.ln1_g[lane * 4 + 256 * j], b4 = *(const float4*)&p.ln1_b[lane * 4 + 256 * j];
.Lxb7_done:
.LBB0_1161:
	s_or_b64 exec, exec, s[0:1]
	v_readlane_b32 s0, v240, 42
	s_movk_i32 s22, 0x3ff
	s_cmpk_gt_i32 s0, 0x3ff
	v_lshlrev_b32_e32 v148, 2, v129
	s_waitcnt lgkmcnt(0)
	s_barrier
	v_readlane_b32 s1, v240, 43
	s_cbranch_scc1 .LBB0_1208
	v_readlane_b32 s36, v240, 26
	v_and_b32_e32 v4, 12, v135
	v_readlane_b32 s37, v240, 27
	v_and_b32_e32 v1, 63, v128
	v_mov_b32_e32 v49, 0
	v_lshl_or_b32 v16, v129, 4, v4
	v_readlane_b32 s38, v240, 28
	v_readlane_b32 s39, v240, 29
	v_readlane_b32 s40, v240, 30
	v_readlane_b32 s41, v240, 31
	v_readlane_b32 s42, v240, 32
	v_readlane_b32 s43, v240, 33
	s_mov_b64 s[12:13], s[36:37]
	v_lshlrev_b32_e32 v2, 8, v129
	v_mul_u32_u24_e32 v21, 0x140, v16
	v_lshlrev_b32_e32 v16, 4, v1
	v_mov_b32_e32 v17, v49
	s_mov_b64 s[14:15], s[38:39]
	v_or_b32_e32 v5, v2, v4
	v_lshl_add_u64 v[52:53], s[12:13], 0, v[16:17]
	v_lshl_add_u64 v[54:55], s[14:15], 0, v[16:17]
	v_lshlrev_b32_e32 v16, 3, v1
	v_or_b32_e32 v6, 1, v5
	v_lshlrev_b32_e32 v50, 2, v136
	s_mov_b64 s[18:19], s[42:43]
	v_lshl_add_u64 v[56:57], s[56:57], 0, v[16:17]
	v_lshlrev_b32_e32 v16, 2, v5
	v_mov_b32_e32 v51, v49
	v_lshlrev_b32_e32 v48, 8, v6
	v_or_b32_e32 v10, 2, v5
	v_lshl_add_u64 v[58:59], s[12:13], 0, v[16:17]
	v_lshl_add_u64 v[60:61], s[14:15], 0, v[16:17]
	v_lshl_add_u64 v[16:17], s[18:19], 0, v[50:51]
	v_lshlrev_b32_e32 v0, 2, v1
	v_cmp_eq_u32_e64 s[6:7], 0, v1
	v_lshlrev_b32_e32 v8, 8, v10
	v_mov_b32_e32 v9, v49
	s_mov_b64 s[16:17], s[40:41]
	v_lshl_add_u64 v[64:65], v[16:17], 0, v[48:49]
	v_lshlrev_b32_e32 v48, 5, v5
	v_or_b32_e32 v1, 32, v5
	v_lshlrev_b32_e32 v6, 5, v6
	v_mov_b32_e32 v7, v49
	v_lshl_add_u64 v[66:67], v[16:17], 0, v[8:9]
	v_lshl_add_u64 v[8:9], s[16:17], 0, v[48:49]
	v_lshlrev_b32_e32 v48, 5, v1
	v_lshlrev_b32_e32 v10, 5, v10
	v_mov_b32_e32 v11, v49
	v_or_b32_e32 v14, 3, v5
	v_lshl_add_u64 v[6:7], s[16:17], 0, v[6:7]
	v_lshl_add_u64 v[78:79], s[16:17], 0, v[48:49]
	v_lshlrev_b32_e32 v48, 8, v1
	v_or_b32_e32 v1, 16, v5
	v_lshl_add_u32 v122, v136, 3, 0
	v_lshlrev_b32_e32 v12, 8, v14
	v_lshlrev_b32_e32 v14, 5, v14
	v_mov_b32_e32 v15, v49
	s_movk_i32 s0, 0x120
	v_lshl_add_u64 v[72:73], v[6:7], 0, v[50:51]
	v_lshl_add_u64 v[6:7], s[16:17], 0, v[10:11]
	v_lshl_add_u64 v[80:81], s[18:19], 0, v[48:49]
	v_lshlrev_b32_e32 v48, 8, v1
	v_lshlrev_b32_e32 v3, 5, v129
	v_mov_b32_e32 v13, v49
	v_sub_u32_e32 v20, v122, v50
	v_mad_u32_u24 v123, v128, s0, 0
	v_lshlrev_b32_e32 v18, 8, v5
	v_mov_b32_e32 v19, v49
	v_lshl_add_u64 v[74:75], v[6:7], 0, v[50:51]
	v_lshl_add_u64 v[6:7], s[16:17], 0, v[14:15]
	s_mov_b64 s[2:3], 0x400
	v_lshl_add_u64 v[86:87], s[18:19], 0, v[48:49]
	v_lshlrev_b32_e32 v48, 5, v1
	v_readlane_b32 s0, v240, 42
	v_cmp_gt_u32_e64 s[8:9], 8, v136
	v_cmp_gt_u32_e64 s[10:11], 16, v128
	v_lshl_add_u64 v[62:63], v[16:17], 0, v[18:19]
	v_lshl_add_u64 v[68:69], v[16:17], 0, v[12:13]
	v_lshl_add_u64 v[70:71], v[8:9], 0, v[50:51]
	v_lshl_add_u64 v[76:77], v[6:7], 0, v[50:51]
	v_lshl_add_u64 v[82:83], v[8:9], 0, s[2:3]
	v_lshl_add_u64 v[84:85], s[18:19], 0, v[18:19]
	v_lshl_add_u64 v[88:89], s[16:17], 0, v[48:49]
	s_movk_i32 s23, 0x37f
	s_movk_i32 s24, 0x3fc
	v_lshlrev_b32_e32 v48, 2, v0
	s_movk_i32 s25, 0x3fd
	s_movk_i32 s26, 0x3fe
	v_mov_b32_e32 v135, 0x3727c5ac
	s_mov_b32 s27, 0x800000
	v_lshlrev_b32_e32 v90, 2, v2
	v_lshlrev_b32_e32 v92, 2, v4
	s_mov_b64 s[4:5], 0x2000
	v_add_u32_e32 v137, v20, v21
	s_mov_b32 s28, 0xe38f
	s_mov_b32 s29, 0xff61b1e6
	s_mov_b32 s30, 0x3fb8aa3b
	s_mov_b32 s31, 0xc2ce8ed0
	s_mov_b32 s36, 0x42b17218
	v_mov_b32_e32 v138, 1
	v_add_u32_e32 v139, 0, v3
	v_mov_b32_e32 v140, 0xff61b1e6
	v_mov_b32_e32 v141, 0x7f800000
	s_mov_b32 s37, s0
	v_readlane_b32 s44, v240, 34
	v_readlane_b32 s45, v240, 35
	v_readlane_b32 s46, v240, 36
	v_readlane_b32 s47, v240, 37
	v_readlane_b32 s48, v240, 38
	v_readlane_b32 s49, v240, 39
	v_readlane_b32 s50, v240, 40
	v_readlane_b32 s51, v240, 41
	v_readlane_b32 s1, v240, 43
	global_load_dwordx4 v[194:197], v[52:53], off
	global_load_dwordx4 v[198:201], v[52:53], off offset:1024
	global_load_dwordx4 v[202:205], v[52:53], off offset:2048
	global_load_dwordx4 v[206:209], v[52:53], off offset:3072
	global_load_dwordx4 v[210:213], v[54:55], off
	global_load_dwordx4 v[214:217], v[54:55], off offset:1024
	global_load_dwordx4 v[218:221], v[54:55], off offset:2048
	global_load_dwordx4 v[222:225], v[54:55], off offset:3072
	s_waitcnt vmcnt(0)
	s_branch .LBB0_1166

; __device__ void phaseD(const Params& p, char* smem) {
;     ...
; #pragma unroll
;       for (int i = 0; i < 4; i++)
; #pragma unroll
;         for (int j = 0; j < 4; j++) {
;           const int row = row0 + w * 4 + i;
;           const float* zr = ((row & 2047) >= 896) ? (p.Z + (size_t)row * DM) : (p.LF + ((size_t)((row >> 11) * 1024 + (row & 1023))) * DM);
;           v[i][j] = *(const float4*)&zr[lane * 4 + 256 * j];
;         }
; #pragma unroll
;       for (int i = 0; i < 4; i++) {
;         const int row = row0 + w * 4 + i;
;         float s = 0.f;
; #pragma unroll
;         for (int j = 0; j < 4; j++) s += v[i][j].x + v[i][j].y + v[i][j].z + v[i][j].w;
;         const float mu = wave_sum(s) * (1.f / 1024.f);
.LBB0_1166:
	s_lshl_b32 s38, s37, 4
	v_add_u32_e32 v100, s38, v148
	v_ashrrev_i32_e32 v5, 1, v100
	v_and_b32_e32 v6, 0xfffffc00, v5
	v_and_or_b32 v0, v100, s24, v6
	v_ashrrev_i32_e32 v1, 31, v0
	v_ashrrev_i32_e32 v101, 31, v100
	v_and_b32_e32 v4, 0x780, v100
	v_lshlrev_b64 v[0:1], 12, v[0:1]
	v_lshlrev_b64 v[2:3], 12, v[100:101]
	v_lshl_add_u64 v[0:1], s[90:91], 0, v[0:1]
	v_lshl_add_u64 v[2:3], s[94:95], 0, v[2:3]
	v_cmp_lt_u32_e32 vcc, s23, v4
	v_or_b32_e32 v98, 1, v100
	v_or_b32_e32 v96, 2, v100
	v_cndmask_b32_e32 v1, v1, v3, vcc
	v_cndmask_b32_e32 v0, v0, v2, vcc
	v_lshl_add_u64 v[0:1], v[0:1], 0, v[48:49]
	global_load_dwordx4 v[102:105], v[0:1], off
	global_load_dwordx4 v[106:109], v[0:1], off offset:1024
	global_load_dwordx4 v[142:145], v[0:1], off offset:2048
	global_load_dwordx4 v[150:153], v[0:1], off offset:3072
	v_or_b32_e32 v94, 3, v100
	v_bfi_b32 v0, s22, v94, v5
	v_and_or_b32 v2, v98, s25, v6
	v_and_or_b32 v6, v96, s26, v6
	v_ashrrev_i32_e32 v99, 31, v98
	v_ashrrev_i32_e32 v97, 31, v96
	v_ashrrev_i32_e32 v95, 31, v94
	v_ashrrev_i32_e32 v1, 31, v0
	v_ashrrev_i32_e32 v3, 31, v2
	v_ashrrev_i32_e32 v7, 31, v6
	v_lshlrev_b64 v[4:5], 12, v[98:99]
	v_lshlrev_b64 v[8:9], 12, v[96:97]
	v_lshlrev_b64 v[10:11], 12, v[94:95]
	v_lshlrev_b64 v[0:1], 12, v[0:1]
	v_lshlrev_b64 v[2:3], 12, v[2:3]
	v_lshlrev_b64 v[6:7], 12, v[6:7]
	v_lshl_add_u64 v[4:5], s[94:95], 0, v[4:5]
	v_lshl_add_u64 v[8:9], s[94:95], 0, v[8:9]
	v_lshl_add_u64 v[10:11], s[94:95], 0, v[10:11]
	v_lshl_add_u64 v[0:1], s[90:91], 0, v[0:1]
	v_lshl_add_u64 v[2:3], s[90:91], 0, v[2:3]
	v_lshl_add_u64 v[6:7], s[90:91], 0, v[6:7]
	v_cndmask_b32_e32 v3, v3, v5, vcc
	v_cndmask_b32_e32 v2, v2, v4, vcc
	v_cndmask_b32_e32 v5, v7, v9, vcc
	v_cndmask_b32_e32 v4, v6, v8, vcc
	v_cndmask_b32_e32 v1, v1, v11, vcc
	v_cndmask_b32_e32 v0, v0, v10, vcc
	v_lshl_add_u64 v[2:3], v[2:3], 0, v[48:49]
	v_lshl_add_u64 v[4:5], v[4:5], 0, v[48:49]
	v_lshl_add_u64 v[0:1], v[0:1], 0, v[48:49]
	global_load_dwordx4 v[44:47], v[2:3], off
	global_load_dwordx4 v[40:43], v[2:3], off offset:1024
	global_load_dwordx4 v[36:39], v[2:3], off offset:2048
	global_load_dwordx4 v[32:35], v[2:3], off offset:3072
	global_load_dwordx4 v[28:31], v[4:5], off
	global_load_dwordx4 v[24:27], v[4:5], off offset:1024
	global_load_dwordx4 v[20:23], v[4:5], off offset:2048
	global_load_dwordx4 v[16:19], v[4:5], off offset:3072
	global_load_dwordx4 v[12:15], v[0:1], off
	global_load_dwordx4 v[8:11], v[0:1], off offset:1024
	s_nop 0
	global_load_dwordx4 v[4:7], v[0:1], off offset:2048
	s_nop 0
	global_load_dwordx4 v[0:3], v[0:1], off offset:3072
	s_waitcnt vmcnt(15)
	v_mov_b32_e32 v110, v102
	s_waitcnt vmcnt(14)
	v_mov_b32_e32 v111, v106
	v_mov_b32_e32 v112, v103
	v_mov_b32_e32 v113, v107
	v_mov_b32_e32 v114, v104
	v_mov_b32_e32 v115, v108
	v_pk_add_f32 v[110:111], v[110:111], v[112:113]
	v_mov_b32_e32 v116, v105
	v_mov_b32_e32 v117, v109
	s_waitcnt vmcnt(13)
	v_mov_b32_e32 v118, v142
	s_waitcnt vmcnt(12)
	v_mov_b32_e32 v119, v150
	v_mov_b32_e32 v120, v143
	v_mov_b32_e32 v121, v151
	v_pk_add_f32 v[110:111], v[110:111], v[114:115]
	v_mov_b32_e32 v146, v144
	v_mov_b32_e32 v147, v152
	v_pk_add_f32 v[112:113], v[118:119], v[120:121]
	v_pk_add_f32 v[110:111], v[110:111], v[116:117]
	v_mov_b32_e32 v154, v145
	v_mov_b32_e32 v155, v153
	v_pk_add_f32 v[112:113], v[112:113], v[146:147]
	v_add_f32_e32 v91, 0, v110
	v_pk_add_f32 v[112:113], v[112:113], v[154:155]
	v_add_f32_e32 v91, v91, v111
	v_add_f32_e32 v91, v91, v112
	v_add_f32_e32 v91, v91, v113
	s_nop 1
	v_add_f32_dpp v91, v91, v91 row_ror:8 row_mask:0xf bank_mask:0xf bound_ctrl:1
	s_nop 1
	v_add_f32_dpp v91, v91, v91 row_ror:4 row_mask:0xf bank_mask:0xf bound_ctrl:1
	s_nop 1
	v_add_f32_dpp v91, v91, v91 row_ror:2 row_mask:0xf bank_mask:0xf bound_ctrl:1
	s_nop 1
	v_add_f32_dpp v91, v91, v91 row_ror:1 row_mask:0xf bank_mask:0xf bound_ctrl:1
	s_nop 0
	v_readlane_b32 s12, v91, 16
	v_readlane_b32 s13, v91, 48
	v_readlane_b32 s0, v91, 0
	v_readlane_b32 s1, v91, 32
	v_mov_b32_e32 v110, s12
	v_mov_b32_e32 v111, s13
	v_pk_add_f32 v[110:111], s[0:1], v[110:111]
	s_nop 0
	v_add_f32_e32 v91, v110, v111
	v_mul_f32_e32 v120, 0x3a800000, v91
	v_pk_add_f32 v[118:119], v[102:103], v[120:121] op_sel_hi:[1,0] neg_lo:[0,1] neg_hi:[0,1]
	v_pk_add_f32 v[112:113], v[106:107], v[120:121] op_sel_hi:[1,0] neg_lo:[0,1] neg_hi:[0,1]
	v_pk_add_f32 v[116:117], v[104:105], v[120:121] op_sel_hi:[1,0] neg_lo:[0,1] neg_hi:[0,1]
	v_mov_b32_e32 v104, v119
	v_mov_b32_e32 v105, v113
	v_pk_add_f32 v[108:109], v[108:109], v[120:121] op_sel_hi:[1,0] neg_lo:[0,1] neg_hi:[0,1]
	v_mov_b32_e32 v102, v118
	v_mov_b32_e32 v103, v112
	v_pk_mul_f32 v[104:105], v[104:105], v[104:105]
	v_pk_add_f32 v[114:115], v[142:143], v[120:121] op_sel_hi:[1,0] neg_lo:[0,1] neg_hi:[0,1]
	v_pk_fma_f32 v[102:103], v[102:103], v[102:103], v[104:105]
	v_mov_b32_e32 v104, v116
	v_mov_b32_e32 v105, v108
	v_pk_fma_f32 v[102:103], v[104:105], v[104:105], v[102:103]
	v_mov_b32_e32 v104, v117
	v_mov_b32_e32 v105, v109
	v_pk_fma_f32 v[106:107], v[104:105], v[104:105], v[102:103]
	v_pk_add_f32 v[102:103], v[150:151], v[120:121] op_sel_hi:[1,0] neg_lo:[0,1] neg_hi:[0,1]
	v_pk_add_f32 v[110:111], v[144:145], v[120:121] op_sel_hi:[1,0] neg_lo:[0,1] neg_hi:[0,1]
	v_mov_b32_e32 v144, v103
	v_mov_b32_e32 v145, v115
	v_pk_add_f32 v[104:105], v[152:153], v[120:121] op_sel_hi:[1,0] neg_lo:[0,1] neg_hi:[0,1]
	v_mov_b32_e32 v142, v102
	v_mov_b32_e32 v143, v114
	v_pk_mul_f32 v[144:145], v[144:145], v[144:145]
	v_add_f32_e32 v91, v106, v107
	v_pk_fma_f32 v[142:143], v[142:143], v[142:143], v[144:145]
	v_mov_b32_e32 v144, v104
	v_mov_b32_e32 v145, v110
; __device__ void phaseD(const Params& p, char* smem) {
;     ...
;         float q = 0.f;
; #pragma unroll
;         for (int j = 0; j < 4; j++) {
;           v[i][j].x -= mu; v[i][j].y -= mu; v[i][j].z -= mu; v[i][j].w -= mu;
;           q += v[i][j].x * v[i][j].x + v[i][j].y * v[i][j].y + v[i][j].z * v[i][j].z + v[i][j].w * v[i][j].w;
;         }
;         const float rstd = rsqrtf(wave_sum(q) * (1.f / 1024.f) + LN_EPS);
;         if (lane == 0) { stats[(w * 4 + i) * 2] = mu; stats[(w * 4 + i) * 2 + 1] = rstd; }
; #pragma unroll
;         for (int j = 0; j < 4; j++) {
;           const float4 gg = *(const float4*)&p.ln1_g[lane * 4 + 256 * j], b4 = *(const float4*)&p.ln1_b[lane * 4 + 256 * j];
;           const float4 o = make_float4(v[i][j].x * rstd * gg.x + b4.x, v[i][j].y * rstd * gg.y + b4.y, v[i][j].z * rstd * gg.z + b4.z, v[i][j].w * rstd * gg.w + b4.w);
;           uint2 h; h.x = pack2(o.x, o.y); h.y = pack2(o.z, o.w);
;           *(uint2*)&p.X1B[(size_t)row * DM + lane * 4 + 256 * j] = h;
	v_pk_fma_f32 v[142:143], v[144:145], v[144:145], v[142:143]
	v_mov_b32_e32 v144, v105
	v_mov_b32_e32 v145, v111
	v_pk_fma_f32 v[142:143], v[144:145], v[144:145], v[142:143]
	s_nop 0
	v_add_f32_e32 v91, v143, v91
	v_add_f32_e32 v91, v142, v91
	s_nop 1
	v_add_f32_dpp v91, v91, v91 row_ror:8 row_mask:0xf bank_mask:0xf bound_ctrl:1
	s_nop 1
	v_add_f32_dpp v91, v91, v91 row_ror:4 row_mask:0xf bank_mask:0xf bound_ctrl:1
	s_nop 1
	v_add_f32_dpp v91, v91, v91 row_ror:2 row_mask:0xf bank_mask:0xf bound_ctrl:1
	s_nop 1
	v_add_f32_dpp v91, v91, v91 row_ror:1 row_mask:0xf bank_mask:0xf bound_ctrl:1
	s_nop 0
	v_readlane_b32 s12, v91, 16
	v_readlane_b32 s13, v91, 48
	v_readlane_b32 s0, v91, 0
	v_readlane_b32 s1, v91, 32
	v_mov_b32_e32 v106, s12
	v_mov_b32_e32 v107, s13
	v_pk_add_f32 v[106:107], s[0:1], v[106:107]
	s_nop 0
	v_add_f32_e32 v91, v106, v107
	v_fmamk_f32 v91, v91, 0x3a800000, v135
	v_mul_f32_e32 v93, 0x4b800000, v91
	v_cmp_gt_f32_e32 vcc, s27, v91
	s_nop 1
	v_cndmask_b32_e32 v91, v91, v93, vcc
	v_rsq_f32_e32 v91, v91
	s_nop 0
	v_mul_f32_e32 v93, 0x45800000, v91
	v_cndmask_b32_e32 v106, v91, v93, vcc
	s_and_saveexec_b64 s[0:1], s[6:7]
	v_mov_b32_e32 v121, v106
	ds_write_b64 v139, v[120:121] offset:25088
	s_or_b64 exec, exec, s[0:1]
	v_lshlrev_b64 v[100:101], 11, v[100:101]
	v_pk_mul_f32 v[118:119], v[118:119], v[106:107] op_sel_hi:[1,0]
	v_pk_mul_f32 v[116:117], v[116:117], v[106:107] op_sel_hi:[1,0]
	v_lshl_add_u64 v[120:121], v[56:57], 0, v[100:101]
	v_pk_mul_f32 v[108:109], v[108:109], v[106:107] op_sel_hi:[1,0]
	s_waitcnt vmcnt(11)
	v_mov_b32_e32 v146, v44
	s_waitcnt vmcnt(10)
	v_mov_b32_e32 v147, v40
	v_mov_b32_e32 v154, v47
	v_mov_b32_e32 v155, v43
	s_waitcnt vmcnt(9)
	v_mov_b32_e32 v156, v36
	s_waitcnt vmcnt(8)
	v_mov_b32_e32 v157, v32
	v_mov_b32_e32 v158, v37
	v_mov_b32_e32 v159, v33
	v_mov_b32_e32 v172, v38
	v_mov_b32_e32 v173, v34
	v_mov_b32_e32 v174, v39
	v_mov_b32_e32 v175, v35
	s_waitcnt vmcnt(0)
	v_pk_fma_f32 v[100:101], v[118:119], v[194:195], v[210:211]
	v_pk_fma_f32 v[116:117], v[116:117], v[196:197], v[212:213]
	v_cvt_pk_bf16_f32 v100, v100, v101
	v_cvt_pk_bf16_f32 v101, v116, v117
	global_store_dwordx2 v[120:121], v[100:101], off
	v_pk_mul_f32 v[100:101], v[112:113], v[106:107] op_sel_hi:[1,0]
	v_mov_b32_e32 v150, v45
	v_mov_b32_e32 v151, v41
	v_mov_b32_e32 v152, v46
	v_mov_b32_e32 v153, v42
	v_pk_fma_f32 v[100:101], v[100:101], v[198:199], v[214:215]
	v_pk_fma_f32 v[108:109], v[108:109], v[200:201], v[216:217]
	v_cvt_pk_bf16_f32 v100, v100, v101
	v_cvt_pk_bf16_f32 v101, v108, v109
	global_store_dwordx2 v[120:121], v[100:101], off offset:512
	v_pk_mul_f32 v[100:101], v[114:115], v[106:107] op_sel_hi:[1,0]
	v_pk_mul_f32 v[108:109], v[110:111], v[106:107] op_sel_hi:[1,0]
	v_pk_fma_f32 v[100:101], v[100:101], v[202:203], v[218:219]
	v_pk_fma_f32 v[108:109], v[108:109], v[204:205], v[220:221]
	v_cvt_pk_bf16_f32 v100, v100, v101
	v_cvt_pk_bf16_f32 v101, v108, v109
	global_store_dwordx2 v[120:121], v[100:101], off offset:1024
	v_pk_add_f32 v[100:101], v[146:147], v[150:151]
	v_pk_add_f32 v[108:109], v[156:157], v[158:159]
	v_pk_add_f32 v[100:101], v[100:101], v[152:153]
	v_pk_add_f32 v[108:109], v[108:109], v[172:173]
	v_pk_add_f32 v[100:101], v[100:101], v[154:155]
	v_pk_add_f32 v[108:109], v[108:109], v[174:175]
	v_add_f32_e32 v91, 0, v100
	v_add_f32_e32 v91, v91, v101
	v_add_f32_e32 v91, v91, v108
	v_add_f32_e32 v91, v91, v109
	s_nop 1
	v_add_f32_dpp v91, v91, v91 row_ror:8 row_mask:0xf bank_mask:0xf bound_ctrl:1
	s_nop 1
	v_add_f32_dpp v91, v91, v91 row_ror:4 row_mask:0xf bank_mask:0xf bound_ctrl:1
	s_nop 1
	v_add_f32_dpp v91, v91, v91 row_ror:2 row_mask:0xf bank_mask:0xf bound_ctrl:1
	s_nop 1
	v_add_f32_dpp v91, v91, v91 row_ror:1 row_mask:0xf bank_mask:0xf bound_ctrl:1
	s_nop 0
	v_readlane_b32 s12, v91, 16
	v_readlane_b32 s13, v91, 48
	v_readlane_b32 s0, v91, 0
	v_readlane_b32 s1, v91, 32
	v_mov_b32_e32 v100, s12
	v_mov_b32_e32 v101, s13
	v_pk_add_f32 v[100:101], s[0:1], v[100:101]
	s_nop 0
	v_add_f32_e32 v91, v100, v101
	v_mul_f32_e32 v108, 0x3a800000, v91
	v_pk_add_f32 v[100:101], v[44:45], v[108:109] op_sel_hi:[1,0] neg_lo:[0,1] neg_hi:[0,1]
	v_pk_add_f32 v[44:45], v[40:41], v[108:109] op_sel_hi:[1,0] neg_lo:[0,1] neg_hi:[0,1]
	v_pk_add_f32 v[40:41], v[42:43], v[108:109] op_sel_hi:[1,0] neg_lo:[0,1] neg_hi:[0,1]
	v_pk_add_f32 v[42:43], v[36:37], v[108:109] op_sel_hi:[1,0] neg_lo:[0,1] neg_hi:[0,1]
	v_pk_add_f32 v[32:33], v[32:33], v[108:109] op_sel_hi:[1,0] neg_lo:[0,1] neg_hi:[0,1]
	v_mov_b32_e32 v118, v101
	v_mov_b32_e32 v119, v45
	v_pk_add_f32 v[46:47], v[46:47], v[108:109] op_sel_hi:[1,0] neg_lo:[0,1] neg_hi:[0,1]
	v_mov_b32_e32 v36, v100
	v_mov_b32_e32 v37, v44
	v_mov_b32_e32 v150, v33
	v_mov_b32_e32 v151, v43
	v_pk_mul_f32 v[118:119], v[118:119], v[118:119]
	v_pk_add_f32 v[38:39], v[38:39], v[108:109] op_sel_hi:[1,0] neg_lo:[0,1] neg_hi:[0,1]
	v_pk_add_f32 v[34:35], v[34:35], v[108:109] op_sel_hi:[1,0] neg_lo:[0,1] neg_hi:[0,1]
	v_mov_b32_e32 v142, v46
	v_mov_b32_e32 v143, v40
	v_mov_b32_e32 v146, v32
	v_mov_b32_e32 v147, v42
	v_pk_mul_f32 v[150:151], v[150:151], v[150:151]
	v_pk_fma_f32 v[36:37], v[36:37], v[36:37], v[118:119]
	v_mov_b32_e32 v144, v47
	v_mov_b32_e32 v145, v41
	v_mov_b32_e32 v152, v34
	v_mov_b32_e32 v153, v38
	v_pk_fma_f32 v[118:119], v[146:147], v[146:147], v[150:151]
	v_pk_fma_f32 v[36:37], v[142:143], v[142:143], v[36:37]
	v_mov_b32_e32 v154, v35
	v_mov_b32_e32 v155, v39
	v_pk_fma_f32 v[118:119], v[152:153], v[152:153], v[118:119]
	v_pk_fma_f32 v[36:37], v[144:145], v[144:145], v[36:37]
	v_pk_fma_f32 v[118:119], v[154:155], v[154:155], v[118:119]
	v_add_f32_e32 v36, v36, v37
; __device__ void phaseD(const Params& p, char* smem) {
;     ...
;       for (int i = 0; i < 4; i++) {
;         const int row = row0 + w * 4 + i;
;         float s = 0.f;
; #pragma unroll
;         for (int j = 0; j < 4; j++) s += v[i][j].x + v[i][j].y + v[i][j].z + v[i][j].w;
;         const float mu = wave_sum(s) * (1.f / 1024.f);
;         float q = 0.f;
; #pragma unroll
;         for (int j = 0; j < 4; j++) {
;           v[i][j].x -= mu; v[i][j].y -= mu; v[i][j].z -= mu; v[i][j].w -= mu;
;           q += v[i][j].x * v[i][j].x + v[i][j].y * v[i][j].y + v[i][j].z * v[i][j].z + v[i][j].w * v[i][j].w;
;         }
;         const float rstd = rsqrtf(wave_sum(q) * (1.f / 1024.f) + LN_EPS);
;         if (lane == 0) { stats[(w * 4 + i) * 2] = mu; stats[(w * 4 + i) * 2 + 1] = rstd; }
; #pragma unroll
;         for (int j = 0; j < 4; j++) {
;           const float4 gg = *(const float4*)&p.ln1_g[lane * 4 + 256 * j], b4 = *(const float4*)&p.ln1_b[lane * 4 + 256 * j];
;           const float4 o = make_float4(v[i][j].x * rstd * gg.x + b4.x, v[i][j].y * rstd * gg.y + b4.y, v[i][j].z * rstd * gg.z + b4.z, v[i][j].w * rstd * gg.w + b4.w);
;           uint2 h; h.x = pack2(o.x, o.y); h.y = pack2(o.z, o.w);
;           *(uint2*)&p.X1B[(size_t)row * DM + lane * 4 + 256 * j] = h;
	v_add_f32_e32 v36, v119, v36
	v_add_f32_e32 v36, v118, v36
	s_nop 1
	v_add_f32_dpp v36, v36, v36 row_ror:8 row_mask:0xf bank_mask:0xf bound_ctrl:1
	s_nop 1
	v_add_f32_dpp v36, v36, v36 row_ror:4 row_mask:0xf bank_mask:0xf bound_ctrl:1
	s_nop 1
	v_add_f32_dpp v36, v36, v36 row_ror:2 row_mask:0xf bank_mask:0xf bound_ctrl:1
	s_nop 1
	v_add_f32_dpp v36, v36, v36 row_ror:1 row_mask:0xf bank_mask:0xf bound_ctrl:1
	s_nop 0
	v_readlane_b32 s12, v36, 16
	v_readlane_b32 s13, v36, 48
	v_readlane_b32 s0, v36, 0
	v_readlane_b32 s1, v36, 32
	v_mov_b32_e32 v36, s12
	v_mov_b32_e32 v37, s13
	v_pk_add_f32 v[36:37], s[0:1], v[36:37]
	s_nop 0
	v_add_f32_e32 v36, v36, v37
	v_fmamk_f32 v36, v36, 0x3a800000, v135
	v_mul_f32_e32 v37, 0x4b800000, v36
	v_cmp_gt_f32_e32 vcc, s27, v36
	s_nop 1
	v_cndmask_b32_e32 v36, v36, v37, vcc
	v_rsq_f32_e32 v91, v36
	v_pk_mul_f32 v[36:37], v[102:103], v[106:107] op_sel_hi:[1,0]
	v_pk_mul_f32 v[102:103], v[104:105], v[106:107] op_sel_hi:[1,0]
	v_pk_fma_f32 v[36:37], v[36:37], v[206:207], v[222:223]
	v_pk_fma_f32 v[102:103], v[102:103], v[208:209], v[224:225]
	v_mul_f32_e32 v93, 0x45800000, v91
	v_cvt_pk_bf16_f32 v36, v36, v37
	v_cvt_pk_bf16_f32 v37, v102, v103
	global_store_dwordx2 v[120:121], v[36:37], off offset:1536
	v_cndmask_b32_e32 v36, v91, v93, vcc
	s_and_saveexec_b64 s[0:1], s[6:7]
	v_mov_b32_e32 v109, v36
	ds_write_b64 v139, v[108:109] offset:25096
	s_or_b64 exec, exec, s[0:1]
	v_lshlrev_b64 v[98:99], 11, v[98:99]
	v_pk_mul_f32 v[100:101], v[100:101], v[36:37] op_sel_hi:[1,0]
	v_pk_mul_f32 v[46:47], v[46:47], v[36:37] op_sel_hi:[1,0]
	v_lshl_add_u64 v[110:111], v[56:57], 0, v[98:99]
	v_pk_mul_f32 v[44:45], v[44:45], v[36:37] op_sel_hi:[1,0]
	v_pk_mul_f32 v[40:41], v[40:41], v[36:37] op_sel_hi:[1,0]
	v_pk_mul_f32 v[38:39], v[38:39], v[36:37] op_sel_hi:[1,0]
	v_mov_b32_e32 v112, v20
	v_mov_b32_e32 v113, v16
	v_mov_b32_e32 v114, v21
	v_mov_b32_e32 v115, v17
	v_mov_b32_e32 v116, v22
	v_mov_b32_e32 v117, v18
	v_mov_b32_e32 v118, v23
	v_mov_b32_e32 v119, v19
	v_pk_fma_f32 v[98:99], v[100:101], v[194:195], v[210:211]
	v_pk_fma_f32 v[46:47], v[46:47], v[196:197], v[212:213]
	v_cvt_pk_bf16_f32 v98, v98, v99
	v_cvt_pk_bf16_f32 v99, v46, v47
	global_store_dwordx2 v[110:111], v[98:99], off
	v_mov_b32_e32 v106, v30
	v_mov_b32_e32 v107, v26
	v_mov_b32_e32 v108, v31
	v_mov_b32_e32 v109, v27
	v_pk_fma_f32 v[44:45], v[44:45], v[198:199], v[214:215]
	v_pk_fma_f32 v[40:41], v[40:41], v[200:201], v[216:217]
	v_cvt_pk_bf16_f32 v44, v44, v45
	v_cvt_pk_bf16_f32 v45, v40, v41
	global_store_dwordx2 v[110:111], v[44:45], off offset:512
	v_pk_mul_f32 v[40:41], v[42:43], v[36:37] op_sel_hi:[1,0]
	v_mov_b32_e32 v102, v28
	v_mov_b32_e32 v103, v24
	v_mov_b32_e32 v104, v29
	v_mov_b32_e32 v105, v25
	v_pk_fma_f32 v[40:41], v[40:41], v[202:203], v[218:219]
	v_pk_fma_f32 v[38:39], v[38:39], v[204:205], v[220:221]
	v_cvt_pk_bf16_f32 v40, v40, v41
	v_cvt_pk_bf16_f32 v41, v38, v39
	global_store_dwordx2 v[110:111], v[40:41], off offset:1024
	v_pk_add_f32 v[38:39], v[102:103], v[104:105]
	v_pk_add_f32 v[40:41], v[112:113], v[114:115]
	v_pk_add_f32 v[38:39], v[38:39], v[106:107]
	v_pk_add_f32 v[40:41], v[40:41], v[116:117]
	v_pk_add_f32 v[38:39], v[38:39], v[108:109]
	v_pk_add_f32 v[40:41], v[40:41], v[118:119]
	v_add_f32_e32 v37, 0, v38
	v_add_f32_e32 v37, v37, v39
	v_add_f32_e32 v37, v37, v40
	v_add_f32_e32 v37, v37, v41
	s_nop 1
	v_add_f32_dpp v37, v37, v37 row_ror:8 row_mask:0xf bank_mask:0xf bound_ctrl:1
	s_nop 1
	v_add_f32_dpp v37, v37, v37 row_ror:4 row_mask:0xf bank_mask:0xf bound_ctrl:1
	s_nop 1
	v_add_f32_dpp v37, v37, v37 row_ror:2 row_mask:0xf bank_mask:0xf bound_ctrl:1
	s_nop 1
	v_add_f32_dpp v37, v37, v37 row_ror:1 row_mask:0xf bank_mask:0xf bound_ctrl:1
	s_nop 0
	v_readlane_b32 s12, v37, 16
	v_readlane_b32 s13, v37, 48
	v_readlane_b32 s0, v37, 0
	v_readlane_b32 s1, v37, 32
	v_mov_b32_e32 v38, s12
	v_mov_b32_e32 v39, s13
	v_pk_add_f32 v[38:39], s[0:1], v[38:39]
	s_nop 0
	v_add_f32_e32 v37, v38, v39
	v_mul_f32_e32 v40, 0x3a800000, v37
	v_pk_add_f32 v[38:39], v[28:29], v[40:41] op_sel_hi:[1,0] neg_lo:[0,1] neg_hi:[0,1]
	v_pk_add_f32 v[28:29], v[24:25], v[40:41] op_sel_hi:[1,0] neg_lo:[0,1] neg_hi:[0,1]
	v_pk_add_f32 v[24:25], v[26:27], v[40:41] op_sel_hi:[1,0] neg_lo:[0,1] neg_hi:[0,1]
	v_pk_add_f32 v[26:27], v[20:21], v[40:41] op_sel_hi:[1,0] neg_lo:[0,1] neg_hi:[0,1]
	v_pk_add_f32 v[16:17], v[16:17], v[40:41] op_sel_hi:[1,0] neg_lo:[0,1] neg_hi:[0,1]
	v_mov_b32_e32 v46, v39
	v_mov_b32_e32 v47, v29
	v_pk_add_f32 v[30:31], v[30:31], v[40:41] op_sel_hi:[1,0] neg_lo:[0,1] neg_hi:[0,1]
	v_mov_b32_e32 v20, v38
	v_mov_b32_e32 v21, v28
	v_mov_b32_e32 v108, v17
	v_mov_b32_e32 v109, v27
	v_pk_mul_f32 v[46:47], v[46:47], v[46:47]
	v_pk_add_f32 v[22:23], v[22:23], v[40:41] op_sel_hi:[1,0] neg_lo:[0,1] neg_hi:[0,1]
	v_pk_add_f32 v[18:19], v[18:19], v[40:41] op_sel_hi:[1,0] neg_lo:[0,1] neg_hi:[0,1]
	v_mov_b32_e32 v102, v30
	v_mov_b32_e32 v103, v24
	v_mov_b32_e32 v106, v16
	v_mov_b32_e32 v107, v26
	v_pk_mul_f32 v[108:109], v[108:109], v[108:109]
	v_pk_fma_f32 v[20:21], v[20:21], v[20:21], v[46:47]
	v_mov_b32_e32 v104, v31
	v_mov_b32_e32 v105, v25
	v_mov_b32_e32 v112, v18
	v_mov_b32_e32 v113, v22
	v_pk_fma_f32 v[46:47], v[106:107], v[106:107], v[108:109]
	v_pk_fma_f32 v[20:21], v[102:103], v[102:103], v[20:21]
	v_mov_b32_e32 v114, v19
	v_mov_b32_e32 v115, v23
	v_pk_fma_f32 v[46:47], v[112:113], v[112:113], v[46:47]
	v_pk_fma_f32 v[20:21], v[104:105], v[104:105], v[20:21]
	v_pk_fma_f32 v[46:47], v[114:115], v[114:115], v[46:47]
	v_add_f32_e32 v20, v20, v21
	v_add_f32_e32 v20, v47, v20
	v_add_f32_e32 v20, v46, v20
	s_nop 1
; __device__ void phaseD(const Params& p, char* smem) {
;     ...
;       for (int i = 0; i < 4; i++) {
;         const int row = row0 + w * 4 + i;
;         float s = 0.f;
; #pragma unroll
;         for (int j = 0; j < 4; j++) s += v[i][j].x + v[i][j].y + v[i][j].z + v[i][j].w;
;         const float mu = wave_sum(s) * (1.f / 1024.f);
;         float q = 0.f;
; #pragma unroll
;         for (int j = 0; j < 4; j++) {
;           v[i][j].x -= mu; v[i][j].y -= mu; v[i][j].z -= mu; v[i][j].w -= mu;
;           q += v[i][j].x * v[i][j].x + v[i][j].y * v[i][j].y + v[i][j].z * v[i][j].z + v[i][j].w * v[i][j].w;
;         }
;         const float rstd = rsqrtf(wave_sum(q) * (1.f / 1024.f) + LN_EPS);
;         if (lane == 0) { stats[(w * 4 + i) * 2] = mu; stats[(w * 4 + i) * 2 + 1] = rstd; }
; #pragma unroll
;         for (int j = 0; j < 4; j++) {
;           const float4 gg = *(const float4*)&p.ln1_g[lane * 4 + 256 * j], b4 = *(const float4*)&p.ln1_b[lane * 4 + 256 * j];
;           const float4 o = make_float4(v[i][j].x * rstd * gg.x + b4.x, v[i][j].y * rstd * gg.y + b4.y, v[i][j].z * rstd * gg.z + b4.z, v[i][j].w * rstd * gg.w + b4.w);
;           uint2 h; h.x = pack2(o.x, o.y); h.y = pack2(o.z, o.w);
;           *(uint2*)&p.X1B[(size_t)row * DM + lane * 4 + 256 * j] = h;
	v_add_f32_dpp v20, v20, v20 row_ror:8 row_mask:0xf bank_mask:0xf bound_ctrl:1
	s_nop 1
	v_add_f32_dpp v20, v20, v20 row_ror:4 row_mask:0xf bank_mask:0xf bound_ctrl:1
	s_nop 1
	v_add_f32_dpp v20, v20, v20 row_ror:2 row_mask:0xf bank_mask:0xf bound_ctrl:1
	s_nop 1
	v_add_f32_dpp v20, v20, v20 row_ror:1 row_mask:0xf bank_mask:0xf bound_ctrl:1
	s_nop 0
	v_readlane_b32 s12, v20, 16
	v_readlane_b32 s13, v20, 48
	v_readlane_b32 s0, v20, 0
	v_readlane_b32 s1, v20, 32
	v_mov_b32_e32 v20, s12
	v_mov_b32_e32 v21, s13
	v_pk_add_f32 v[20:21], s[0:1], v[20:21]
	s_nop 0
	v_add_f32_e32 v20, v20, v21
	v_fmamk_f32 v20, v20, 0x3a800000, v135
	v_mul_f32_e32 v21, 0x4b800000, v20
	v_cmp_gt_f32_e32 vcc, s27, v20
	s_nop 1
	v_cndmask_b32_e32 v20, v20, v21, vcc
	v_rsq_f32_e32 v37, v20
	s_nop 0
	v_pk_mul_f32 v[20:21], v[32:33], v[36:37] op_sel_hi:[1,0]
	v_pk_mul_f32 v[32:33], v[34:35], v[36:37] op_sel_hi:[1,0]
	v_pk_fma_f32 v[20:21], v[20:21], v[206:207], v[222:223]
	v_pk_fma_f32 v[32:33], v[32:33], v[208:209], v[224:225]
	v_mul_f32_e32 v34, 0x45800000, v37
	v_cvt_pk_bf16_f32 v20, v20, v21
	v_cvt_pk_bf16_f32 v21, v32, v33
	global_store_dwordx2 v[110:111], v[20:21], off offset:1536
	v_cndmask_b32_e32 v20, v37, v34, vcc
	s_and_saveexec_b64 s[0:1], s[6:7]
	v_mov_b32_e32 v41, v20
	ds_write_b64 v139, v[40:41] offset:25104
	s_or_b64 exec, exec, s[0:1]
	v_pk_mul_f32 v[38:39], v[38:39], v[20:21] op_sel_hi:[1,0]
	v_pk_mul_f32 v[30:31], v[30:31], v[20:21] op_sel_hi:[1,0]
	v_lshlrev_b64 v[36:37], 11, v[96:97]
	v_lshl_add_u64 v[44:45], v[56:57], 0, v[36:37]
	v_pk_mul_f32 v[28:29], v[28:29], v[20:21] op_sel_hi:[1,0]
	v_pk_mul_f32 v[24:25], v[24:25], v[20:21] op_sel_hi:[1,0]
	v_pk_mul_f32 v[22:23], v[22:23], v[20:21] op_sel_hi:[1,0]
	v_mov_b32_e32 v46, v4
	v_mov_b32_e32 v47, v0
	v_mov_b32_e32 v96, v5
	v_mov_b32_e32 v97, v1
	v_mov_b32_e32 v98, v6
	v_mov_b32_e32 v99, v2
	v_mov_b32_e32 v100, v7
	v_mov_b32_e32 v101, v3
	v_pk_fma_f32 v[32:33], v[38:39], v[194:195], v[210:211]
	v_pk_fma_f32 v[30:31], v[30:31], v[196:197], v[212:213]
	v_cvt_pk_bf16_f32 v32, v32, v33
	v_cvt_pk_bf16_f32 v33, v30, v31
	global_store_dwordx2 v[44:45], v[32:33], off
	v_mov_b32_e32 v38, v13
	v_mov_b32_e32 v39, v9
	v_mov_b32_e32 v40, v14
	v_mov_b32_e32 v41, v10
	v_mov_b32_e32 v42, v15
	v_mov_b32_e32 v43, v11
	v_pk_fma_f32 v[28:29], v[28:29], v[198:199], v[214:215]
	v_pk_fma_f32 v[24:25], v[24:25], v[200:201], v[216:217]
	v_cvt_pk_bf16_f32 v28, v28, v29
	v_cvt_pk_bf16_f32 v29, v24, v25
	global_store_dwordx2 v[44:45], v[28:29], off offset:512
	v_pk_mul_f32 v[24:25], v[26:27], v[20:21] op_sel_hi:[1,0]
	v_mov_b32_e32 v36, v12
	v_mov_b32_e32 v37, v8
	v_pk_fma_f32 v[24:25], v[24:25], v[202:203], v[218:219]
	v_pk_fma_f32 v[22:23], v[22:23], v[204:205], v[220:221]
	v_cvt_pk_bf16_f32 v24, v24, v25
	v_cvt_pk_bf16_f32 v25, v22, v23
	global_store_dwordx2 v[44:45], v[24:25], off offset:1024
	v_pk_add_f32 v[22:23], v[36:37], v[38:39]
	v_pk_add_f32 v[24:25], v[46:47], v[96:97]
	v_pk_add_f32 v[22:23], v[22:23], v[40:41]
	v_pk_add_f32 v[24:25], v[24:25], v[98:99]
	v_pk_add_f32 v[22:23], v[22:23], v[42:43]
	v_pk_add_f32 v[24:25], v[24:25], v[100:101]
	v_add_f32_e32 v21, 0, v22
	v_add_f32_e32 v21, v21, v23
	v_add_f32_e32 v21, v21, v24
	v_add_f32_e32 v21, v21, v25
	s_nop 1
	v_add_f32_dpp v21, v21, v21 row_ror:8 row_mask:0xf bank_mask:0xf bound_ctrl:1
	s_nop 1
	v_add_f32_dpp v21, v21, v21 row_ror:4 row_mask:0xf bank_mask:0xf bound_ctrl:1
	s_nop 1
	v_add_f32_dpp v21, v21, v21 row_ror:2 row_mask:0xf bank_mask:0xf bound_ctrl:1
	s_nop 1
	v_add_f32_dpp v21, v21, v21 row_ror:1 row_mask:0xf bank_mask:0xf bound_ctrl:1
	s_nop 0
	v_readlane_b32 s12, v21, 16
	v_readlane_b32 s13, v21, 48
	v_readlane_b32 s0, v21, 0
	v_readlane_b32 s1, v21, 32
	v_mov_b32_e32 v22, s12
	v_mov_b32_e32 v23, s13
	v_pk_add_f32 v[22:23], s[0:1], v[22:23]
	s_nop 0
	v_add_f32_e32 v21, v22, v23
	v_mul_f32_e32 v24, 0x3a800000, v21
	v_pk_add_f32 v[22:23], v[12:13], v[24:25] op_sel_hi:[1,0] neg_lo:[0,1] neg_hi:[0,1]
	v_pk_add_f32 v[12:13], v[8:9], v[24:25] op_sel_hi:[1,0] neg_lo:[0,1] neg_hi:[0,1]
	v_pk_add_f32 v[8:9], v[10:11], v[24:25] op_sel_hi:[1,0] neg_lo:[0,1] neg_hi:[0,1]
	v_pk_add_f32 v[10:11], v[4:5], v[24:25] op_sel_hi:[1,0] neg_lo:[0,1] neg_hi:[0,1]
	v_pk_add_f32 v[4:5], v[0:1], v[24:25] op_sel_hi:[1,0] neg_lo:[0,1] neg_hi:[0,1]
	v_mov_b32_e32 v34, v23
	v_mov_b32_e32 v35, v13
	v_pk_add_f32 v[14:15], v[14:15], v[24:25] op_sel_hi:[1,0] neg_lo:[0,1] neg_hi:[0,1]
	v_pk_add_f32 v[0:1], v[2:3], v[24:25] op_sel_hi:[1,0] neg_lo:[0,1] neg_hi:[0,1]
	v_mov_b32_e32 v2, v22
	v_mov_b32_e32 v3, v12
	v_mov_b32_e32 v42, v5
	v_mov_b32_e32 v43, v11
; __device__ void phaseD(const Params& p, char* smem) {
;     ...
;       for (int i = 0; i < 4; i++) {
;         const int row = row0 + w * 4 + i;
;         float s = 0.f;
; #pragma unroll
;         for (int j = 0; j < 4; j++) s += v[i][j].x + v[i][j].y + v[i][j].z + v[i][j].w;
;         const float mu = wave_sum(s) * (1.f / 1024.f);
;         float q = 0.f;
; #pragma unroll
;         for (int j = 0; j < 4; j++) {
;           v[i][j].x -= mu; v[i][j].y -= mu; v[i][j].z -= mu; v[i][j].w -= mu;
;           q += v[i][j].x * v[i][j].x + v[i][j].y * v[i][j].y + v[i][j].z * v[i][j].z + v[i][j].w * v[i][j].w;
;         }
;         const float rstd = rsqrtf(wave_sum(q) * (1.f / 1024.f) + LN_EPS);
;         if (lane == 0) { stats[(w * 4 + i) * 2] = mu; stats[(w * 4 + i) * 2 + 1] = rstd; }
; #pragma unroll
;         for (int j = 0; j < 4; j++) {
;           const float4 gg = *(const float4*)&p.ln1_g[lane * 4 + 256 * j], b4 = *(const float4*)&p.ln1_b[lane * 4 + 256 * j];
;           const float4 o = make_float4(v[i][j].x * rstd * gg.x + b4.x, v[i][j].y * rstd * gg.y + b4.y, v[i][j].z * rstd * gg.z + b4.z, v[i][j].w * rstd * gg.w + b4.w);
;           uint2 h; h.x = pack2(o.x, o.y); h.y = pack2(o.z, o.w);
;           *(uint2*)&p.X1B[(size_t)row * DM + lane * 4 + 256 * j] = h;
;         }
;       }
;     }
;     __syncthreads();
;     f32x4 acc[5];
; #pragma unroll
;     for (int i = 0; i < 5; i++) acc[i] = f32x4{0, 0, 0, 0};
;     const int rrow = row0 + l15;
;     const float* xrow = (((rrow & 2047) >= 896) ? (p.Z + (size_t)rrow * DM) : (p.LF + ((size_t)((rrow >> 11) * 1024 + (rrow & 1023))) * DM)) + 256 * w + 4 * kg;
;     const float rmu = stats[l15 * 2], rrs = stats[l15 * 2 + 1];
;     struct RB { float4 a, g, b; float we[4][4]; float wg[4]; };
;     auto rload = [&](int it, RB& r) {
;       r.a = *(const float4*)&xrow[16 * it];
;       r.g = *(const float4*)&p.ln1_g[256 * w + 16 * it + 4 * kg];
;       r.b = *(const float4*)&p.ln1_b[256 * w + 16 * it + 4 * kg];
	v_pk_mul_f32 v[34:35], v[34:35], v[34:35]
	v_pk_add_f32 v[6:7], v[6:7], v[24:25] op_sel_hi:[1,0] neg_lo:[0,1] neg_hi:[0,1]
	v_mov_b32_e32 v36, v14
	v_mov_b32_e32 v37, v8
	v_mov_b32_e32 v40, v4
	v_mov_b32_e32 v41, v10
	v_pk_mul_f32 v[42:43], v[42:43], v[42:43]
	v_pk_fma_f32 v[2:3], v[2:3], v[2:3], v[34:35]
	v_mov_b32_e32 v38, v15
	v_mov_b32_e32 v39, v9
	v_mov_b32_e32 v46, v0
	v_mov_b32_e32 v47, v6
	v_pk_fma_f32 v[34:35], v[40:41], v[40:41], v[42:43]
	v_pk_fma_f32 v[2:3], v[36:37], v[36:37], v[2:3]
	v_mov_b32_e32 v96, v1
	v_mov_b32_e32 v97, v7
	v_pk_fma_f32 v[34:35], v[46:47], v[46:47], v[34:35]
	v_pk_fma_f32 v[2:3], v[38:39], v[38:39], v[2:3]
	v_pk_fma_f32 v[34:35], v[96:97], v[96:97], v[34:35]
	v_add_f32_e32 v2, v2, v3
	v_add_f32_e32 v2, v35, v2
	v_add_f32_e32 v2, v34, v2
	s_nop 1
	v_add_f32_dpp v2, v2, v2 row_ror:8 row_mask:0xf bank_mask:0xf bound_ctrl:1
	s_nop 1
	v_add_f32_dpp v2, v2, v2 row_ror:4 row_mask:0xf bank_mask:0xf bound_ctrl:1
	s_nop 1
	v_add_f32_dpp v2, v2, v2 row_ror:2 row_mask:0xf bank_mask:0xf bound_ctrl:1
	s_nop 1
	v_add_f32_dpp v2, v2, v2 row_ror:1 row_mask:0xf bank_mask:0xf bound_ctrl:1
	s_nop 0
	v_readlane_b32 s12, v2, 16
	v_readlane_b32 s13, v2, 48
	v_readlane_b32 s0, v2, 0
	v_readlane_b32 s1, v2, 32
	v_mov_b32_e32 v2, s12
	v_mov_b32_e32 v3, s13
	v_pk_add_f32 v[2:3], s[0:1], v[2:3]
	s_nop 0
	v_add_f32_e32 v2, v2, v3
	v_fmamk_f32 v2, v2, 0x3a800000, v135
	v_mul_f32_e32 v3, 0x4b800000, v2
	v_cmp_gt_f32_e32 vcc, s27, v2
	s_nop 1
	v_cndmask_b32_e32 v2, v2, v3, vcc
	v_rsq_f32_e32 v21, v2
	s_nop 0
	v_pk_mul_f32 v[2:3], v[16:17], v[20:21] op_sel_hi:[1,0]
	v_pk_mul_f32 v[16:17], v[18:19], v[20:21] op_sel_hi:[1,0]
	v_pk_fma_f32 v[2:3], v[2:3], v[206:207], v[222:223]
	v_pk_fma_f32 v[16:17], v[16:17], v[208:209], v[224:225]
	v_mul_f32_e32 v18, 0x45800000, v21
	v_cvt_pk_bf16_f32 v2, v2, v3
	v_cvt_pk_bf16_f32 v3, v16, v17
	global_store_dwordx2 v[44:45], v[2:3], off offset:1536
	v_cndmask_b32_e32 v2, v21, v18, vcc
	s_and_saveexec_b64 s[0:1], s[6:7]
	v_mov_b32_e32 v25, v2
	ds_write_b64 v139, v[24:25] offset:25112
	s_or_b64 exec, exec, s[0:1]
	v_pk_mul_f32 v[22:23], v[22:23], v[2:3] op_sel_hi:[1,0]
	v_pk_mul_f32 v[14:15], v[14:15], v[2:3] op_sel_hi:[1,0]
	v_lshlrev_b64 v[20:21], 11, v[94:95]
	v_lshl_add_u64 v[28:29], v[56:57], 0, v[20:21]
	v_pk_mul_f32 v[12:13], v[12:13], v[2:3] op_sel_hi:[1,0]
	v_pk_mul_f32 v[8:9], v[8:9], v[2:3] op_sel_hi:[1,0]
	v_pk_mul_f32 v[6:7], v[6:7], v[2:3] op_sel_hi:[1,0]
	s_and_b32 s0, s38, 0x780
	s_cmpk_gt_u32 s0, 0x37f
	s_cselect_b64 vcc, -1, 0
	s_lshl_b32 s0, s37, 3
	v_pk_mul_f32 v[4:5], v[4:5], v[2:3] op_sel_hi:[1,0]
	v_pk_mul_f32 v[0:1], v[0:1], v[2:3] op_sel_hi:[1,0]
	v_mov_b32_e32 v91, v49
	v_mov_b32_e32 v93, v49
	v_mov_b32_e32 v118, 0
	v_mov_b32_e32 v119, 0
	v_pk_fma_f32 v[16:17], v[22:23], v[194:195], v[210:211]
	v_pk_fma_f32 v[14:15], v[14:15], v[196:197], v[212:213]
	v_cvt_pk_bf16_f32 v16, v16, v17
	v_cvt_pk_bf16_f32 v17, v14, v15
	global_store_dwordx2 v[28:29], v[16:17], off
	v_pk_fma_f32 v[12:13], v[12:13], v[198:199], v[214:215]
	v_pk_fma_f32 v[8:9], v[8:9], v[200:201], v[216:217]
	v_cvt_pk_bf16_f32 v12, v12, v13
	v_cvt_pk_bf16_f32 v13, v8, v9
	global_store_dwordx2 v[28:29], v[12:13], off offset:512
	v_pk_mul_f32 v[8:9], v[10:11], v[2:3] op_sel_hi:[1,0]
	v_or_b32_e32 v2, s38, v136
	v_mov_b32_e32 v3, s0
	v_bfi_b32 v3, s22, v2, v3
	v_cndmask_b32_e32 v2, v3, v2, vcc
	s_and_b64 s[0:1], vcc, exec
	v_ashrrev_i32_e32 v3, 31, v2
	s_cselect_b32 s1, s95, s91
	s_cselect_b32 s0, s94, s90
	v_lshlrev_b64 v[2:3], 12, v[2:3]
	v_lshl_add_u64 v[2:3], s[0:1], 0, v[2:3]
	v_lshl_add_u64 v[2:3], v[2:3], 0, v[90:91]
	v_lshl_add_u64 v[44:45], v[2:3], 0, v[92:93]
	v_pk_fma_f32 v[8:9], v[8:9], v[202:203], v[218:219]
	v_pk_fma_f32 v[6:7], v[6:7], v[204:205], v[220:221]
	v_cvt_pk_bf16_f32 v8, v8, v9
	v_cvt_pk_bf16_f32 v9, v6, v7
	global_store_dwordx2 v[28:29], v[8:9], off offset:1024
	v_pk_fma_f32 v[2:3], v[4:5], v[206:207], v[222:223]
	v_pk_fma_f32 v[0:1], v[0:1], v[208:209], v[224:225]
	v_cvt_pk_bf16_f32 v2, v2, v3
	v_cvt_pk_bf16_f32 v3, v0, v1
	global_store_dwordx2 v[28:29], v[2:3], off offset:1536
	s_waitcnt lgkmcnt(0)
	s_barrier
	global_load_dwordx4 v[0:3], v[44:45], off
	global_load_dwordx4 v[4:7], v[58:59], off
	global_load_dwordx4 v[8:11], v[60:61], off
	global_load_dword v91, v[62:63], off
	global_load_dword v93, v[62:63], off offset:64
	global_load_dword v116, v[62:63], off offset:128
	global_load_dword v117, v[62:63], off offset:192
	ds_read_b64 v[46:47], v122 offset:25088
	s_and_saveexec_b64 s[0:1], s[8:9]
	s_cbranch_execz .LBB0_1176
	global_load_dword v119, v[70:71], off

; __device__ void phaseE2(const Params& p, char* smem) {
;     ...
;     auto epi = [&](f32x4 (&acc)[4][4], int mb, int nb) {
; #pragma unroll
;       for (int mi = 0; mi < 4; mi++) {
;         const int r = mb + mi * 16;
;         if (r < rows) {
;           const float gt = lg[r];
; #pragma unroll
.LBB0_1364:
	v_lshlrev_b32_e32 v80, 15, v80
	s_waitcnt vmcnt(31)
	v_ashrrev_i32_e32 v99, 31, v98
	v_lshl_add_u64 v[32:33], v[80:81], 2, s[70:71]
	v_lshl_add_u64 v[32:33], v[98:99], 2, v[32:33]
	v_cmp_lt_i32_e32 vcc, v126, v118
	v_lshlrev_b32_e32 v80, 2, v126
	v_lshl_add_u64 v[34:35], v[32:33], 0, v[80:81]
	global_load_dword v132, v[34:35], off
	global_load_dword v134, v[34:35], off offset:64
	global_load_dword v136, v[34:35], off offset:128
	global_load_dword v138, v[34:35], off offset:192
	s_waitcnt vmcnt(0)
	s_and_saveexec_b64 s[18:19], vcc
	s_cbranch_execnz .LBB0_1370
	s_or_b64 exec, exec, s[18:19]
	v_cmp_lt_i32_e32 vcc, v166, v118
	s_and_saveexec_b64 s[18:19], vcc
	s_cbranch_execnz .LBB0_1371

; __device__ void phaseE2(const Params& p, char* smem) {
;     ...
;       for (int mi = 0; mi < 4; mi++) {
;         const int r = mb + mi * 16;
;         if (r < rows) {
;           const float gt = lg[r];
; #pragma unroll
;           for (int ni = 0; ni < 4; ni++) {
;             f32x4 v = acc[mi][ni];
;             uint2 o; o.x = pack2(gt * v[0], gt * v[1]); o.y = pack2(gt * v[2], gt * v[3]);
;             *(uint2*)&p.Y[(size_t)(slot0 + r) * DM + n0 + nb + ni * 16] = o;
;           }
;         }
.LBB0_1367:
	v_mov_b32_e32 v34, v136
	v_add_u32_e32 v36, v117, v167
	v_ashrrev_i32_e32 v37, 31, v36
	v_lshlrev_b64 v[36:37], 11, v[36:37]
	v_lshl_add_u64 v[36:37], v[94:95], 0, v[36:37]
	v_pk_mul_f32 v[28:29], v[28:29], v[34:35] op_sel_hi:[1,0]
	v_pk_mul_f32 v[30:31], v[30:31], v[34:35] op_sel_hi:[1,0]
	v_pk_mul_f32 v[24:25], v[24:25], v[34:35] op_sel_hi:[1,0]
	v_pk_mul_f32 v[26:27], v[26:27], v[34:35] op_sel_hi:[1,0]
	v_pk_mul_f32 v[20:21], v[20:21], v[34:35] op_sel_hi:[1,0]
	v_pk_mul_f32 v[22:23], v[22:23], v[34:35] op_sel_hi:[1,0]
	v_pk_mul_f32 v[16:17], v[16:17], v[34:35] op_sel_hi:[1,0]
	v_pk_mul_f32 v[18:19], v[18:19], v[34:35] op_sel_hi:[1,0]
	v_cvt_pk_bf16_f32 v28, v28, v29
	v_cvt_pk_bf16_f32 v29, v30, v31
	v_cvt_pk_bf16_f32 v24, v24, v25
	v_cvt_pk_bf16_f32 v25, v26, v27
	v_cvt_pk_bf16_f32 v20, v20, v21
	v_cvt_pk_bf16_f32 v21, v22, v23
	v_cvt_pk_bf16_f32 v16, v16, v17
	v_cvt_pk_bf16_f32 v17, v18, v19
	global_store_dwordx2 v[36:37], v[28:29], off
	global_store_dwordx2 v[36:37], v[24:25], off offset:32
	global_store_dwordx2 v[36:37], v[20:21], off offset:64
	global_store_dwordx2 v[36:37], v[16:17], off offset:96
.LBB0_1368:
	s_or_b64 exec, exec, s[18:19]
	v_cmp_lt_i32_e32 vcc, v168, v118
	s_and_saveexec_b64 s[18:19], vcc
	s_xor_b64 s[18:19], exec, s[18:19]
	s_cbranch_execz .LBB0_1349
	v_mov_b32_e32 v16, v138
	v_add_u32_e32 v18, v117, v168
	v_ashrrev_i32_e32 v19, 31, v18
	v_lshlrev_b64 v[18:19], 11, v[18:19]
	v_lshl_add_u64 v[18:19], v[94:95], 0, v[18:19]
	v_pk_mul_f32 v[12:13], v[12:13], v[16:17] op_sel_hi:[1,0]
	v_pk_mul_f32 v[14:15], v[14:15], v[16:17] op_sel_hi:[1,0]
	v_pk_mul_f32 v[8:9], v[8:9], v[16:17] op_sel_hi:[1,0]
	v_pk_mul_f32 v[10:11], v[10:11], v[16:17] op_sel_hi:[1,0]
	v_pk_mul_f32 v[4:5], v[4:5], v[16:17] op_sel_hi:[1,0]
	v_pk_mul_f32 v[6:7], v[6:7], v[16:17] op_sel_hi:[1,0]
	v_pk_mul_f32 v[0:1], v[0:1], v[16:17] op_sel_hi:[1,0]
	v_pk_mul_f32 v[2:3], v[2:3], v[16:17] op_sel_hi:[1,0]
	v_cvt_pk_bf16_f32 v12, v12, v13
	v_cvt_pk_bf16_f32 v13, v14, v15
	v_cvt_pk_bf16_f32 v8, v8, v9
	v_cvt_pk_bf16_f32 v9, v10, v11
	v_cvt_pk_bf16_f32 v4, v4, v5
	v_cvt_pk_bf16_f32 v5, v6, v7
	v_cvt_pk_bf16_f32 v0, v0, v1
	v_cvt_pk_bf16_f32 v1, v2, v3
	global_store_dwordx2 v[18:19], v[12:13], off
	global_store_dwordx2 v[18:19], v[8:9], off offset:32
	global_store_dwordx2 v[18:19], v[4:5], off offset:64
	global_store_dwordx2 v[18:19], v[0:1], off offset:96
	s_branch .LBB0_1349
.LBB0_1370:
	v_mov_b32_e32 v34, v132
	v_add_u32_e32 v36, v117, v126
	v_ashrrev_i32_e32 v37, 31, v36
	v_lshlrev_b64 v[36:37], 11, v[36:37]
	v_lshl_add_u64 v[36:37], v[94:95], 0, v[36:37]
	v_pk_mul_f32 v[38:39], v[64:65], v[34:35] op_sel_hi:[1,0]
	v_pk_mul_f32 v[40:41], v[66:67], v[34:35] op_sel_hi:[1,0]
	v_pk_mul_f32 v[42:43], v[76:77], v[34:35] op_sel_hi:[1,0]
	v_pk_mul_f32 v[44:45], v[78:79], v[34:35] op_sel_hi:[1,0]
	v_pk_mul_f32 v[46:47], v[72:73], v[34:35] op_sel_hi:[1,0]
	v_pk_mul_f32 v[64:65], v[74:75], v[34:35] op_sel_hi:[1,0]
	v_pk_mul_f32 v[66:67], v[68:69], v[34:35] op_sel_hi:[1,0]
	v_pk_mul_f32 v[34:35], v[70:71], v[34:35] op_sel_hi:[1,0]
	v_cvt_pk_bf16_f32 v38, v38, v39
	v_cvt_pk_bf16_f32 v39, v40, v41
	v_cvt_pk_bf16_f32 v40, v42, v43
	v_cvt_pk_bf16_f32 v41, v44, v45
	v_cvt_pk_bf16_f32 v42, v46, v47
	v_cvt_pk_bf16_f32 v43, v64, v65
	v_cvt_pk_bf16_f32 v44, v66, v67
	v_cvt_pk_bf16_f32 v45, v34, v35
	global_store_dwordx2 v[36:37], v[38:39], off
	global_store_dwordx2 v[36:37], v[40:41], off offset:32
	global_store_dwordx2 v[36:37], v[42:43], off offset:64
	global_store_dwordx2 v[36:37], v[44:45], off offset:96
	s_or_b64 exec, exec, s[18:19]
	v_cmp_lt_i32_e32 vcc, v166, v118
	s_and_saveexec_b64 s[18:19], vcc
	s_cbranch_execz .LBB0_1366
.LBB0_1371:
	v_mov_b32_e32 v34, v134
	v_add_u32_e32 v36, v117, v166
	v_ashrrev_i32_e32 v37, 31, v36
	v_lshlrev_b64 v[36:37], 11, v[36:37]
	v_lshl_add_u64 v[36:37], v[94:95], 0, v[36:37]
	v_pk_mul_f32 v[38:39], v[60:61], v[34:35] op_sel_hi:[1,0]
	v_pk_mul_f32 v[40:41], v[62:63], v[34:35] op_sel_hi:[1,0]
	v_pk_mul_f32 v[42:43], v[56:57], v[34:35] op_sel_hi:[1,0]
	v_pk_mul_f32 v[44:45], v[58:59], v[34:35] op_sel_hi:[1,0]
	v_pk_mul_f32 v[46:47], v[52:53], v[34:35] op_sel_hi:[1,0]
	v_pk_mul_f32 v[52:53], v[54:55], v[34:35] op_sel_hi:[1,0]
	v_pk_mul_f32 v[48:49], v[48:49], v[34:35] op_sel_hi:[1,0]
	v_pk_mul_f32 v[34:35], v[50:51], v[34:35] op_sel_hi:[1,0]
	v_cvt_pk_bf16_f32 v38, v38, v39
	v_cvt_pk_bf16_f32 v39, v40, v41
	v_cvt_pk_bf16_f32 v40, v42, v43
	v_cvt_pk_bf16_f32 v41, v44, v45
	v_cvt_pk_bf16_f32 v42, v46, v47
	v_cvt_pk_bf16_f32 v43, v52, v53
	v_cvt_pk_bf16_f32 v44, v48, v49
	v_cvt_pk_bf16_f32 v45, v34, v35
	global_store_dwordx2 v[36:37], v[38:39], off
	global_store_dwordx2 v[36:37], v[40:41], off offset:32
	global_store_dwordx2 v[36:37], v[42:43], off offset:64
	global_store_dwordx2 v[36:37], v[44:45], off offset:96
	s_or_b64 exec, exec, s[18:19]
	v_cmp_lt_i32_e32 vcc, v167, v118
	s_and_saveexec_b64 s[18:19], vcc
	s_cbranch_execnz .LBB0_1367
	s_branch .LBB0_1368

; __device__ __forceinline__ float bflo(unsigned v) { return __uint_as_float(v << 16); }
; __device__ __forceinline__ float bfhi(unsigned v) { return __uint_as_float(v & 0xffff0000u); }
; __device__ void phaseF(const Params& p, char* smem) {
;   int* s_off = (int*)(smem + 2 * GEMM_SMEM);
;   int* s_rb = s_off + 72;
;   moe_prefix(p, s_off, s_rb);
;   const int tid = threadIdx.x, lane = tid & 63, w = tid >> 6;
;   for (int rp = blockIdx.x * 4 + w; rp < NTOK / 2; rp += gridDim.x * 4) {
;     int sl[2][2];
; #pragma unroll
;     for (int h = 0; h < 2; h++) {
;       const int row = rp * 2 + h;
;       const int2 te = *(const int2*)&p.tok_e[row * 2], tp = *(const int2*)&p.tok_pos[row * 2];
;       sl[h][0] = s_off[te.x] + tp.x;
;       sl[h][1] = s_off[te.y] + tp.y;
;     }
;     float4 v[2][4];
; #pragma unroll
;     for (int h = 0; h < 2; h++) {
;       const int row = rp * 2 + h;
; #pragma unroll
;       for (int i = 0; i < 4; i++) {
;         const int c = lane * 4 + 256 * i;
;         const uint2 xb2 = *(const uint2*)&p.X1B[(size_t)row * DM + c];
;         const float4 xv = make_float4(bflo(xb2.x), bfhi(xb2.x), bflo(xb2.y), bfhi(xb2.y));
;         const uint2 ya = *(const uint2*)&p.Y[(size_t)sl[h][0] * DM + c];
;         const uint2 yb = *(const uint2*)&p.Y[(size_t)sl[h][1] * DM + c];
.LBB0_1428:
	s_or_b64 exec, exec, s[0:1]
	v_readlane_b32 s2, v240, 42
	s_movk_i32 s0, 0x2000
	s_waitcnt lgkmcnt(0)
	v_lshl_add_u32 v23, s2, 2, v129
	v_cmp_gt_i32_e32 vcc, s0, v23
	s_barrier
	v_readlane_b32 s3, v240, 43
	s_and_saveexec_b64 s[0:1], vcc
	s_cbranch_execz .LBB0_1431
	v_and_b32_e32 v2, 0xfc, v127
	v_readlane_b32 s4, v240, 26
	v_readlane_b32 s0, v240, 1
	v_lshlrev_b32_e32 v0, 2, v2
	v_mov_b32_e32 v1, 0
	v_readlane_b32 s18, v240, 40
	v_readlane_b32 s19, v240, 41
	v_readlane_b32 s1, v240, 2
	v_readlane_b32 s5, v240, 27
	v_readlane_b32 s6, v240, 28
	v_readlane_b32 s7, v240, 29
	v_readlane_b32 s8, v240, 30
	v_readlane_b32 s9, v240, 31
	v_lshl_add_u64 v[8:9], s[18:19], 0, v[0:1]
	v_lshl_add_u64 v[10:11], s[84:85], 0, v[0:1]
	global_load_dwordx4 v[194:197], v[8:9], off
	global_load_dwordx4 v[198:201], v[8:9], off offset:1024
	global_load_dwordx4 v[202:205], v[8:9], off offset:2048
	global_load_dwordx4 v[206:209], v[8:9], off offset:3072
	global_load_dwordx4 v[210:213], v[10:11], off
	global_load_dwordx4 v[214:217], v[10:11], off offset:1024
	global_load_dwordx4 v[218:221], v[10:11], off offset:2048
	global_load_dwordx4 v[222:225], v[10:11], off offset:3072
	v_lshlrev_b32_e32 v2, 1, v2
	v_mov_b32_e32 v3, v1
	v_lshl_add_u64 v[16:17], s[86:87], 0, v[0:1]
	v_lshlrev_b32_e32 v0, 1, v129
	s_lshl_b32 s3, s0, 2
	v_lshl_add_u64 v[12:13], s[56:57], 0, v[2:3]
	v_lshl_add_u64 v[14:15], s[60:61], 0, v[2:3]
	v_lshl_add_u32 v18, s2, 3, v0
	s_lshl_b32 s5, s0, 3
	v_lshl_add_u32 v20, s2, 4, v148
	s_lshl_b32 s6, s0, 4
	s_mov_b64 s[0:1], 0
	s_add_i32 s7, 0, 0x10000
	s_mov_b32 s2, 0x3f9837f0
	s_mov_b32 s4, 0x3a800000
	v_mov_b32_e32 v22, 0x3727c5ac
	s_mov_b32 s8, 0x800000
	s_movk_i32 s9, 0x1fff
	v_readlane_b32 s10, v240, 32
	v_readlane_b32 s11, v240, 33
	v_readlane_b32 s12, v240, 34
	v_readlane_b32 s13, v240, 35
	v_readlane_b32 s14, v240, 36
	v_readlane_b32 s15, v240, 37
	v_readlane_b32 s16, v240, 38
	v_readlane_b32 s17, v240, 39
	s_waitcnt vmcnt(0)
	.p2align 6
.LBB0_1430:
	v_ashrrev_i32_e32 v21, 31, v20
	v_lshlrev_b64 v[4:5], 2, v[20:21]
	v_lshl_add_u64 v[0:1], s[64:65], 0, v[4:5]
	global_load_dwordx4 v[0:3], v[0:1], off
	v_lshl_add_u64 v[4:5], s[66:67], 0, v[4:5]
	global_load_dwordx4 v[4:7], v[4:5], off
	v_ashrrev_i32_e32 v19, 31, v18
	v_lshlrev_b64 v[24:25], 11, v[18:19]
	v_lshl_add_u64 v[26:27], v[12:13], 0, v[24:25]
	v_add_u32_e32 v24, 1, v18
	v_ashrrev_i32_e32 v25, 31, v24
	v_lshlrev_b64 v[34:35], 11, v[24:25]
	v_lshl_add_u64 v[34:35], v[12:13], 0, v[34:35]
	global_load_dwordx2 v[28:29], v[26:27], off
	global_load_dwordx2 v[30:31], v[26:27], off offset:512
	global_load_dwordx2 v[32:33], v[26:27], off offset:1024
	v_lshlrev_b64 v[24:25], 12, v[24:25]
	global_load_dwordx2 v[26:27], v[26:27], off offset:1536
	s_nop 0
	global_load_dwordx2 v[36:37], v[34:35], off
	global_load_dwordx2 v[40:41], v[34:35], off offset:512
	global_load_dwordx2 v[42:43], v[34:35], off offset:1024
	global_load_dwordx2 v[46:47], v[34:35], off offset:1536
	v_lshl_add_u64 v[24:25], v[16:17], 0, v[24:25]
	v_add_u32_e32 v20, s6, v20
	s_waitcnt vmcnt(9)
	v_lshl_add_u32 v0, v0, 2, s7
	v_lshl_add_u32 v1, v1, 2, s7
	ds_read_b32 v21, v0
	ds_read_b32 v0, v1
	v_lshl_add_u32 v1, v2, 2, s7
	v_lshl_add_u32 v2, v3, 2, s7
	ds_read_b32 v34, v1
	ds_read_b32 v35, v2
	s_waitcnt vmcnt(8) lgkmcnt(3)
	v_add_u32_e32 v2, v21, v4
	s_waitcnt lgkmcnt(2)
	v_add_u32_e32 v0, v0, v5
	v_ashrrev_i32_e32 v3, 31, v2
	v_ashrrev_i32_e32 v1, 31, v0
	v_lshlrev_b64 v[2:3], 11, v[2:3]
	s_waitcnt lgkmcnt(1)
	v_add_u32_e32 v6, v34, v6
	v_lshlrev_b64 v[0:1], 11, v[0:1]
	v_lshl_add_u64 v[2:3], v[14:15], 0, v[2:3]
	s_waitcnt lgkmcnt(0)
	v_add_u32_e32 v4, v35, v7
	v_ashrrev_i32_e32 v7, 31, v6
	v_lshl_add_u64 v[0:1], v[14:15], 0, v[0:1]
	global_load_dwordx2 v[48:49], v[2:3], off
	global_load_dwordx2 v[50:51], v[0:1], off
	global_load_dwordx2 v[52:53], v[2:3], off offset:512
	global_load_dwordx2 v[54:55], v[0:1], off offset:512
	global_load_dwordx2 v[56:57], v[2:3], off offset:1024
	global_load_dwordx2 v[58:59], v[0:1], off offset:1024
	global_load_dwordx2 v[60:61], v[2:3], off offset:1536
	global_load_dwordx2 v[62:63], v[0:1], off offset:1536
	v_ashrrev_i32_e32 v5, 31, v4
	v_lshlrev_b64 v[2:3], 11, v[6:7]
	v_lshlrev_b64 v[0:1], 11, v[4:5]
	v_lshl_add_u64 v[34:35], v[14:15], 0, v[2:3]
	v_lshl_add_u64 v[38:39], v[14:15], 0, v[0:1]
	global_load_dwordx2 v[64:65], v[34:35], off
	global_load_dwordx2 v[66:67], v[38:39], off
	global_load_dwordx2 v[68:69], v[34:35], off offset:512
	global_load_dwordx2 v[70:71], v[38:39], off offset:512
	global_load_dwordx2 v[76:77], v[34:35], off offset:1024
	global_load_dwordx2 v[78:79], v[38:39], off offset:1024
	global_load_dwordx2 v[86:87], v[34:35], off offset:1536
	global_load_dwordx2 v[88:89], v[38:39], off offset:1536
	s_waitcnt vmcnt(22)
	v_lshlrev_b32_e32 v80, 16, v30
	v_and_b32_e32 v81, 0xffff0000, v30
	v_lshlrev_b32_e32 v82, 16, v31
	v_and_b32_e32 v83, 0xffff0000, v31
	s_waitcnt vmcnt(21)
	v_lshlrev_b32_e32 v84, 16, v32
	v_and_b32_e32 v85, 0xffff0000, v32
	v_lshlrev_b32_e32 v90, 16, v33
	v_and_b32_e32 v91, 0xffff0000, v33
	s_waitcnt vmcnt(19)
	v_lshlrev_b32_e32 v44, 16, v36
	v_and_b32_e32 v45, 0xffff0000, v36
	v_lshlrev_b32_e32 v38, 16, v37
	v_and_b32_e32 v39, 0xffff0000, v37
	s_waitcnt vmcnt(18)
	v_lshlrev_b32_e32 v36, 16, v40
	v_and_b32_e32 v37, 0xffff0000, v40
	v_lshlrev_b32_e32 v34, 16, v41
	v_and_b32_e32 v35, 0xffff0000, v41
	s_waitcnt vmcnt(17)
	v_lshlrev_b32_e32 v32, 16, v42
	v_and_b32_e32 v33, 0xffff0000, v42
	v_lshlrev_b32_e32 v30, 16, v43
	v_and_b32_e32 v31, 0xffff0000, v43
	v_lshlrev_b32_e32 v72, 16, v28
	v_and_b32_e32 v73, 0xffff0000, v28
	v_lshlrev_b32_e32 v74, 16, v29
	v_and_b32_e32 v75, 0xffff0000, v29
	v_lshlrev_b32_e32 v92, 16, v26
	v_and_b32_e32 v93, 0xffff0000, v26
	v_lshlrev_b32_e32 v94, 16, v27
	v_and_b32_e32 v95, 0xffff0000, v27
	s_waitcnt vmcnt(16)
; __device__ __forceinline__ float bflo(unsigned v) { return __uint_as_float(v << 16); }
; __device__ __forceinline__ float bfhi(unsigned v) { return __uint_as_float(v & 0xffff0000u); }
; __device__ void phaseF(const Params& p, char* smem) {
;     ...
;     for (int h = 0; h < 2; h++) {
;       const int row = rp * 2 + h;
; #pragma unroll
;       for (int i = 0; i < 4; i++) {
;         const int c = lane * 4 + 256 * i;
;         const uint2 xb2 = *(const uint2*)&p.X1B[(size_t)row * DM + c];
;         const float4 xv = make_float4(bflo(xb2.x), bfhi(xb2.x), bflo(xb2.y), bfhi(xb2.y));
;         const uint2 ya = *(const uint2*)&p.Y[(size_t)sl[h][0] * DM + c];
;         const uint2 yb = *(const uint2*)&p.Y[(size_t)sl[h][1] * DM + c];
;         v[h][i].x = ALPHA * xv.x + (bflo(ya.x) + bflo(yb.x));
;         v[h][i].y = ALPHA * xv.y + (bfhi(ya.x) + bfhi(yb.x));
;         v[h][i].z = ALPHA * xv.z + (bflo(ya.y) + bflo(yb.y));
;         v[h][i].w = ALPHA * xv.w + (bfhi(ya.y) + bfhi(yb.y));
;       }
;     }
; #pragma unroll
;     for (int h = 0; h < 2; h++) {
;       const int row = rp * 2 + h;
;       float s = 0.f;
; #pragma unroll
;       for (int i = 0; i < 4; i++) s += v[h][i].x + v[h][i].y + v[h][i].z + v[h][i].w;
;       const float mu = wave_sum(s) * (1.f / 1024.f);
;       float q = 0.f;
	v_lshlrev_b32_e32 v28, 16, v46
	v_and_b32_e32 v29, 0xffff0000, v46
	v_lshlrev_b32_e32 v26, 16, v47
	v_and_b32_e32 v27, 0xffff0000, v47
	s_waitcnt vmcnt(15)
	v_lshlrev_b32_e32 v40, 16, v48
	s_waitcnt vmcnt(14)
	v_lshlrev_b32_e32 v42, 16, v50
	v_and_b32_e32 v41, 0xffff0000, v48
	v_and_b32_e32 v43, 0xffff0000, v50
	s_waitcnt vmcnt(13)
	v_lshlrev_b32_e32 v100, 16, v52
	s_waitcnt vmcnt(12)
	v_lshlrev_b32_e32 v102, 16, v54
	v_and_b32_e32 v101, 0xffff0000, v52
	v_and_b32_e32 v103, 0xffff0000, v54
	v_lshlrev_b32_e32 v96, 16, v49
	v_lshlrev_b32_e32 v98, 16, v51
	v_and_b32_e32 v97, 0xffff0000, v49
	v_and_b32_e32 v99, 0xffff0000, v51
	v_lshlrev_b32_e32 v52, 16, v53
	v_lshlrev_b32_e32 v104, 16, v55
	v_and_b32_e32 v53, 0xffff0000, v53
	v_and_b32_e32 v105, 0xffff0000, v55
	s_waitcnt vmcnt(11)
	v_lshlrev_b32_e32 v106, 16, v56
	s_waitcnt vmcnt(10)
	v_lshlrev_b32_e32 v108, 16, v58
	v_and_b32_e32 v107, 0xffff0000, v56
	v_and_b32_e32 v109, 0xffff0000, v58
	s_waitcnt vmcnt(9)
	v_lshlrev_b32_e32 v110, 16, v60
	v_and_b32_e32 v111, 0xffff0000, v60
	v_lshlrev_b32_e32 v114, 16, v61
	v_and_b32_e32 v115, 0xffff0000, v61
	s_waitcnt vmcnt(6)
	v_lshlrev_b32_e32 v118, 16, v66
	v_and_b32_e32 v119, 0xffff0000, v66
	v_lshlrev_b32_e32 v122, 16, v67
	v_and_b32_e32 v123, 0xffff0000, v67
	s_waitcnt vmcnt(3)
	v_lshlrev_b32_e32 v66, 16, v76
	v_and_b32_e32 v67, 0xffff0000, v76
	v_lshlrev_b32_e32 v60, 16, v77
	v_and_b32_e32 v61, 0xffff0000, v77
	v_pk_add_f32 v[40:41], v[40:41], v[42:43]
	v_pk_add_f32 v[76:77], v[100:101], v[102:103]
	v_lshlrev_b32_e32 v116, 16, v64
	v_and_b32_e32 v117, 0xffff0000, v64
	v_lshlrev_b32_e32 v120, 16, v65
	v_and_b32_e32 v121, 0xffff0000, v65
	v_lshlrev_b32_e32 v124, 16, v68
	v_and_b32_e32 v125, 0xffff0000, v68
	v_lshlrev_b32_e32 v128, 16, v69
	v_and_b32_e32 v129, 0xffff0000, v69
	s_waitcnt vmcnt(2)
	v_lshlrev_b32_e32 v68, 16, v78
	v_and_b32_e32 v69, 0xffff0000, v78
	v_lshlrev_b32_e32 v64, 16, v79
	v_and_b32_e32 v65, 0xffff0000, v79
	v_pk_add_f32 v[42:43], v[96:97], v[98:99]
	v_pk_add_f32 v[52:53], v[52:53], v[104:105]
	v_pk_add_f32 v[78:79], v[106:107], v[108:109]
	v_pk_fma_f32 v[40:41], v[72:73], s[2:3], v[40:41] op_sel_hi:[1,0,1]
	v_pk_fma_f32 v[72:73], v[80:81], s[2:3], v[76:77] op_sel_hi:[1,0,1]
	v_pk_fma_f32 v[42:43], v[74:75], s[2:3], v[42:43] op_sel_hi:[1,0,1]
	v_pk_fma_f32 v[52:53], v[82:83], s[2:3], v[52:53] op_sel_hi:[1,0,1]
	v_pk_fma_f32 v[74:75], v[84:85], s[2:3], v[78:79] op_sel_hi:[1,0,1]
	v_mov_b32_e32 v76, v40
	v_mov_b32_e32 v77, v72
	v_mov_b32_e32 v78, v41
	v_mov_b32_e32 v79, v73
	v_mov_b32_e32 v80, v42
	v_mov_b32_e32 v81, v52
	v_pk_add_f32 v[76:77], v[76:77], v[78:79]
	v_lshlrev_b32_e32 v56, 16, v57
	v_lshlrev_b32_e32 v58, 16, v59
	v_and_b32_e32 v57, 0xffff0000, v57
	v_and_b32_e32 v59, 0xffff0000, v59
	v_mov_b32_e32 v82, v43
	v_mov_b32_e32 v83, v53
	v_pk_add_f32 v[76:77], v[76:77], v[80:81]
	v_lshlrev_b32_e32 v112, 16, v62
	v_and_b32_e32 v113, 0xffff0000, v62
	v_pk_add_f32 v[76:77], v[82:83], v[76:77]
	v_pk_add_f32 v[56:57], v[56:57], v[58:59]
	v_lshlrev_b32_e32 v62, 16, v63
	v_and_b32_e32 v63, 0xffff0000, v63
	v_add_f32_e32 v21, 0, v76
	v_pk_fma_f32 v[58:59], v[90:91], s[2:3], v[56:57] op_sel_hi:[1,0,1]
	v_pk_add_f32 v[56:57], v[110:111], v[112:113]
	v_add_f32_e32 v21, v21, v77
	v_pk_fma_f32 v[76:77], v[92:93], s[2:3], v[56:57] op_sel_hi:[1,0,1]
	v_pk_add_f32 v[56:57], v[114:115], v[62:63]
	v_mov_b32_e32 v62, v75
	v_pk_fma_f32 v[78:79], v[94:95], s[2:3], v[56:57] op_sel_hi:[1,0,1]
	v_mov_b32_e32 v56, v74
	v_mov_b32_e32 v57, v76
	v_mov_b32_e32 v63, v77
	v_pk_add_f32 v[56:57], v[56:57], v[62:63]
	v_mov_b32_e32 v62, v58
	v_mov_b32_e32 v63, v78
	v_pk_add_f32 v[56:57], v[56:57], v[62:63]
	v_mov_b32_e32 v62, v59
	v_mov_b32_e32 v63, v79
	v_pk_add_f32 v[56:57], v[62:63], v[56:57]
	v_lshlrev_b32_e32 v126, 16, v70
	v_add_f32_e32 v21, v21, v56
	v_add_f32_e32 v21, v21, v57
	v_and_b32_e32 v127, 0xffff0000, v70
	v_lshlrev_b32_e32 v70, 16, v71
	v_add_f32_dpp v21, v21, v21 row_ror:8 row_mask:0xf bank_mask:0xf bound_ctrl:1
	v_and_b32_e32 v71, 0xffff0000, v71
	s_waitcnt vmcnt(1)
	v_lshlrev_b32_e32 v50, 16, v86
	v_add_f32_dpp v21, v21, v21 row_ror:4 row_mask:0xf bank_mask:0xf bound_ctrl:1
	s_waitcnt vmcnt(0)
	v_lshlrev_b32_e32 v54, 16, v88
	v_and_b32_e32 v51, 0xffff0000, v86
	v_add_f32_dpp v21, v21, v21 row_ror:2 row_mask:0xf bank_mask:0xf bound_ctrl:1
	v_and_b32_e32 v55, 0xffff0000, v88
	v_pk_add_f32 v[70:71], v[128:129], v[70:71]
	v_add_f32_dpp v21, v21, v21 row_ror:1 row_mask:0xf bank_mask:0xf bound_ctrl:1
	v_lshlrev_b32_e32 v46, 16, v87
	v_readlane_b32 s12, v21, 16
	v_readlane_b32 s13, v21, 48
	v_readlane_b32 s10, v21, 0
	v_readlane_b32 s11, v21, 32
	v_mov_b32_e32 v56, s12
	v_mov_b32_e32 v57, s13
	v_pk_add_f32 v[56:57], s[10:11], v[56:57]
	v_lshlrev_b32_e32 v48, 16, v89
	v_add_f32_e32 v21, v56, v57
	v_mul_f32_e32 v80, 0x3a800000, v21
	v_pk_add_f32 v[82:83], v[40:41], v[80:81] op_sel_hi:[1,0] neg_lo:[0,1] neg_hi:[0,1]
	v_pk_add_f32 v[56:57], v[72:73], v[80:81] op_sel_hi:[1,0] neg_lo:[0,1] neg_hi:[0,1]
	v_pk_add_f32 v[84:85], v[42:43], v[80:81] op_sel_hi:[1,0] neg_lo:[0,1] neg_hi:[0,1]
	v_mov_b32_e32 v42, v83
	v_mov_b32_e32 v43, v57
	v_pk_add_f32 v[52:53], v[52:53], v[80:81] op_sel_hi:[1,0] neg_lo:[0,1] neg_hi:[0,1]
	v_mov_b32_e32 v40, v82
	v_mov_b32_e32 v41, v56
	v_pk_mul_f32 v[42:43], v[42:43], v[42:43]
	v_pk_add_f32 v[62:63], v[74:75], v[80:81] op_sel_hi:[1,0] neg_lo:[0,1] neg_hi:[0,1]
	v_pk_fma_f32 v[40:41], v[40:41], v[40:41], v[42:43]
	v_mov_b32_e32 v42, v84
	v_mov_b32_e32 v43, v52
	v_pk_fma_f32 v[40:41], v[42:43], v[42:43], v[40:41]
	v_mov_b32_e32 v42, v85
	v_mov_b32_e32 v43, v53
	v_pk_fma_f32 v[72:73], v[42:43], v[42:43], v[40:41]
; __device__ void phaseF(const Params& p, char* smem) {
;     ...
; #pragma unroll
;     for (int h = 0; h < 2; h++) {
;       const int row = rp * 2 + h;
;       float s = 0.f;
; #pragma unroll
;       for (int i = 0; i < 4; i++) s += v[h][i].x + v[h][i].y + v[h][i].z + v[h][i].w;
;       const float mu = wave_sum(s) * (1.f / 1024.f);
;       float q = 0.f;
; #pragma unroll
;       for (int i = 0; i < 4; i++) {
;         v[h][i].x -= mu; v[h][i].y -= mu; v[h][i].z -= mu; v[h][i].w -= mu;
;         q += v[h][i].x * v[h][i].x + v[h][i].y * v[h][i].y + v[h][i].z * v[h][i].z + v[h][i].w * v[h][i].w;
;       }
;       const float rstd = rsqrtf(wave_sum(q) * (1.f / 1024.f) + LN_EPS);
	v_pk_add_f32 v[42:43], v[76:77], v[80:81] op_sel_hi:[1,0] neg_lo:[0,1] neg_hi:[0,1]
	v_mov_b32_e32 v77, v63
	v_mov_b32_e32 v76, v43
	v_pk_add_f32 v[58:59], v[58:59], v[80:81] op_sel_hi:[1,0] neg_lo:[0,1] neg_hi:[0,1]
	v_pk_add_f32 v[40:41], v[78:79], v[80:81] op_sel_hi:[1,0] neg_lo:[0,1] neg_hi:[0,1]
	v_mov_b32_e32 v74, v42
	v_mov_b32_e32 v75, v62
	v_pk_mul_f32 v[76:77], v[76:77], v[76:77]
	v_add_f32_e32 v21, v72, v73
	v_pk_fma_f32 v[74:75], v[74:75], v[74:75], v[76:77]
	v_mov_b32_e32 v76, v40
	v_mov_b32_e32 v77, v58
	v_pk_fma_f32 v[74:75], v[76:77], v[76:77], v[74:75]
	v_mov_b32_e32 v76, v41
	v_mov_b32_e32 v77, v59
	v_pk_fma_f32 v[74:75], v[76:77], v[76:77], v[74:75]
	v_and_b32_e32 v47, 0xffff0000, v87
	v_add_f32_e32 v21, v75, v21
	v_add_f32_e32 v21, v74, v21
	v_pk_add_f32 v[74:75], v[116:117], v[118:119]
	v_and_b32_e32 v49, 0xffff0000, v89
	v_pk_fma_f32 v[44:45], v[44:45], s[2:3], v[74:75] op_sel_hi:[1,0,1]
	v_pk_add_f32 v[74:75], v[120:121], v[122:123]
	v_add_f32_dpp v21, v21, v21 row_ror:8 row_mask:0xf bank_mask:0xf bound_ctrl:1
	v_pk_fma_f32 v[38:39], v[38:39], s[2:3], v[74:75] op_sel_hi:[1,0,1]
	v_pk_add_f32 v[74:75], v[124:125], v[126:127]
	v_pk_fma_f32 v[34:35], v[34:35], s[2:3], v[70:71] op_sel_hi:[1,0,1]
	v_pk_fma_f32 v[36:37], v[36:37], s[2:3], v[74:75] op_sel_hi:[1,0,1]
	v_mov_b32_e32 v70, v44
	v_mov_b32_e32 v71, v36
	v_mov_b32_e32 v74, v45
	v_mov_b32_e32 v75, v37
	v_pk_add_f32 v[66:67], v[66:67], v[68:69]
	v_pk_add_f32 v[50:51], v[50:51], v[54:55]
	v_add_f32_dpp v21, v21, v21 row_ror:4 row_mask:0xf bank_mask:0xf bound_ctrl:1
	v_pk_add_f32 v[70:71], v[70:71], v[74:75]
	v_mov_b32_e32 v74, v38
	v_mov_b32_e32 v75, v34
	v_pk_fma_f32 v[32:33], v[32:33], s[2:3], v[66:67] op_sel_hi:[1,0,1]
	v_pk_add_f32 v[60:61], v[60:61], v[64:65]
	v_pk_fma_f32 v[28:29], v[28:29], s[2:3], v[50:51] op_sel_hi:[1,0,1]
	v_pk_add_f32 v[46:47], v[46:47], v[48:49]
	v_add_f32_dpp v21, v21, v21 row_ror:2 row_mask:0xf bank_mask:0xf bound_ctrl:1
	v_pk_add_f32 v[70:71], v[70:71], v[74:75]
	v_mov_b32_e32 v74, v39
	v_mov_b32_e32 v75, v35
	v_pk_fma_f32 v[30:31], v[30:31], s[2:3], v[60:61] op_sel_hi:[1,0,1]
	v_pk_fma_f32 v[26:27], v[26:27], s[2:3], v[46:47] op_sel_hi:[1,0,1]
	v_mov_b32_e32 v46, v32
	v_mov_b32_e32 v47, v28
	v_mov_b32_e32 v48, v33
	v_mov_b32_e32 v49, v29
	v_add_f32_dpp v21, v21, v21 row_ror:1 row_mask:0xf bank_mask:0xf bound_ctrl:1
	v_pk_add_f32 v[70:71], v[74:75], v[70:71]
	v_pk_add_f32 v[46:47], v[46:47], v[48:49]
	v_mov_b32_e32 v48, v30
	v_mov_b32_e32 v49, v26
	v_readlane_b32 s10, v21, 0
	v_readlane_b32 s12, v21, 16
	v_readlane_b32 s11, v21, 32
	v_readlane_b32 s13, v21, 48
	v_add_f32_e32 v21, 0, v70
	v_pk_add_f32 v[46:47], v[46:47], v[48:49]
	v_mov_b32_e32 v48, v31
	v_mov_b32_e32 v49, v27
	v_add_f32_e32 v21, v21, v71
	v_pk_add_f32 v[46:47], v[48:49], v[46:47]
	v_mov_b32_e32 v72, s12
	v_add_f32_e32 v21, v21, v46
	v_add_f32_e32 v21, v21, v47
	v_mov_b32_e32 v73, s13
	v_pk_add_f32 v[72:73], s[10:11], v[72:73]
	v_add_f32_dpp v21, v21, v21 row_ror:8 row_mask:0xf bank_mask:0xf bound_ctrl:1
	s_nop 1
	v_add_f32_dpp v21, v21, v21 row_ror:4 row_mask:0xf bank_mask:0xf bound_ctrl:1
	s_nop 1
	v_add_f32_dpp v21, v21, v21 row_ror:2 row_mask:0xf bank_mask:0xf bound_ctrl:1
	s_nop 1
	v_add_f32_dpp v21, v21, v21 row_ror:1 row_mask:0xf bank_mask:0xf bound_ctrl:1
	s_nop 0
	v_readlane_b32 s12, v21, 16
	v_readlane_b32 s13, v21, 48
	v_readlane_b32 s10, v21, 0
	v_readlane_b32 s11, v21, 32
	v_mov_b32_e32 v46, s12
	v_mov_b32_e32 v47, s13
	v_pk_add_f32 v[46:47], s[10:11], v[46:47]
	s_nop 0
	v_add_f32_e32 v21, v46, v47
	v_mul_f32_e32 v46, 0x3a800000, v21
	v_pk_add_f32 v[44:45], v[44:45], v[46:47] op_sel_hi:[1,0] neg_lo:[0,1] neg_hi:[0,1]
	v_pk_add_f32 v[36:37], v[36:37], v[46:47] op_sel_hi:[1,0] neg_lo:[0,1] neg_hi:[0,1]
	v_mov_b32_e32 v50, v45
	v_mov_b32_e32 v51, v37
	v_pk_add_f32 v[38:39], v[38:39], v[46:47] op_sel_hi:[1,0] neg_lo:[0,1] neg_hi:[0,1]
	v_pk_add_f32 v[34:35], v[34:35], v[46:47] op_sel_hi:[1,0] neg_lo:[0,1] neg_hi:[0,1]
	v_mov_b32_e32 v48, v44
	v_mov_b32_e32 v49, v36
	v_pk_mul_f32 v[50:51], v[50:51], v[50:51]
	v_pk_add_f32 v[32:33], v[32:33], v[46:47] op_sel_hi:[1,0] neg_lo:[0,1] neg_hi:[0,1]
	v_pk_fma_f32 v[48:49], v[48:49], v[48:49], v[50:51]
	v_mov_b32_e32 v50, v38
	v_mov_b32_e32 v51, v34
	v_pk_fma_f32 v[48:49], v[50:51], v[50:51], v[48:49]
	v_mov_b32_e32 v50, v39
	v_mov_b32_e32 v51, v35
	v_pk_add_f32 v[28:29], v[28:29], v[46:47] op_sel_hi:[1,0] neg_lo:[0,1] neg_hi:[0,1]
; __device__ void phaseF(const Params& p, char* smem) {
;     ...
;       const float rstd = rsqrtf(wave_sum(q) * (1.f / 1024.f) + LN_EPS);
; #pragma unroll
;       for (int i = 0; i < 4; i++) {
;         const int c = lane * 4 + 256 * i;
;         const float4 gg = *(const float4*)&p.ln2_g[c], b4 = *(const float4*)&p.ln2_b[c];
;         *(float4*)&p.out[(size_t)row * DM + c] =
;             make_float4(v[h][i].x * rstd * gg.x + b4.x, v[h][i].y * rstd * gg.y + b4.y, v[h][i].z * rstd * gg.z + b4.z, v[h][i].w * rstd * gg.w + b4.w);
;       }
	v_pk_fma_f32 v[48:49], v[50:51], v[50:51], v[48:49]
	v_mov_b32_e32 v50, v29
	v_mov_b32_e32 v51, v33
	v_pk_add_f32 v[30:31], v[30:31], v[46:47] op_sel_hi:[1,0] neg_lo:[0,1] neg_hi:[0,1]
	v_pk_add_f32 v[26:27], v[26:27], v[46:47] op_sel_hi:[1,0] neg_lo:[0,1] neg_hi:[0,1]
	v_mov_b32_e32 v46, v28
	v_mov_b32_e32 v47, v32
	v_pk_mul_f32 v[50:51], v[50:51], v[50:51]
	v_add_f32_e32 v21, v48, v49
	v_pk_fma_f32 v[46:47], v[46:47], v[46:47], v[50:51]
	v_mov_b32_e32 v50, v26
	v_mov_b32_e32 v51, v30
	v_pk_fma_f32 v[46:47], v[50:51], v[50:51], v[46:47]
	v_mov_b32_e32 v50, v27
	v_mov_b32_e32 v51, v31
	v_pk_fma_f32 v[46:47], v[50:51], v[50:51], v[46:47]
	v_mov_b32_e32 v49, v72
	v_add_f32_e32 v21, v47, v21
	v_add_f32_e32 v21, v46, v21
	s_nop 1
	v_add_f32_dpp v21, v21, v21 row_ror:8 row_mask:0xf bank_mask:0xf bound_ctrl:1
	s_nop 1
	v_add_f32_dpp v21, v21, v21 row_ror:4 row_mask:0xf bank_mask:0xf bound_ctrl:1
	s_nop 1
	v_add_f32_dpp v21, v21, v21 row_ror:2 row_mask:0xf bank_mask:0xf bound_ctrl:1
	s_nop 1
	v_add_f32_dpp v21, v21, v21 row_ror:1 row_mask:0xf bank_mask:0xf bound_ctrl:1
	s_nop 0
	v_readlane_b32 s12, v21, 16
	v_readlane_b32 s13, v21, 48
	v_readlane_b32 s10, v21, 0
	v_readlane_b32 s11, v21, 32
	v_mov_b32_e32 v46, s12
	v_mov_b32_e32 v47, s13
	v_pk_add_f32 v[46:47], s[10:11], v[46:47]
	s_nop 0
	v_mov_b32_e32 v48, v46
	v_mov_b32_e32 v72, v47
	v_pk_add_f32 v[46:47], v[48:49], v[72:73]
	v_lshlrev_b64 v[48:49], 12, v[18:19]
	v_pk_fma_f32 v[46:47], v[46:47], s[4:5], v[22:23] op_sel_hi:[1,0,0]
	v_lshl_add_u64 v[48:49], v[16:17], 0, v[48:49]
	v_mul_f32_e32 v21, 0x4b800000, v47
	v_cmp_gt_f32_e32 vcc, s8, v47
	v_add_u32_e32 v23, s3, v23
	v_add_u32_e32 v18, s5, v18
	v_cndmask_b32_e32 v21, v47, v21, vcc
	v_rsq_f32_e32 v21, v21
	s_nop 0
	v_mul_f32_e32 v19, 0x45800000, v21
	v_cndmask_b32_e32 v50, v21, v19, vcc
	v_pk_mul_f32 v[54:55], v[82:83], v[50:51] op_sel_hi:[1,0]
	v_pk_mul_f32 v[42:43], v[42:43], v[50:51] op_sel_hi:[1,0]
	v_pk_fma_f32 v[0:1], v[194:195], v[54:55], v[210:211]
	v_pk_mul_f32 v[4:5], v[84:85], v[50:51] op_sel_hi:[1,0]
	v_pk_mul_f32 v[54:55], v[56:57], v[50:51] op_sel_hi:[1,0]
	v_pk_fma_f32 v[2:3], v[196:197], v[4:5], v[212:213]
	global_store_dwordx4 v[48:49], v[0:3], off
	s_nop 1
	v_pk_mul_f32 v[40:41], v[40:41], v[50:51] op_sel_hi:[1,0]
	v_mul_f32_e32 v19, 0x4b800000, v46
	v_cmp_gt_f32_e32 vcc, s8, v46
	v_pk_fma_f32 v[0:1], v[54:55], v[198:199], v[214:215]
	v_pk_mul_f32 v[4:5], v[52:53], v[50:51] op_sel_hi:[1,0]
	v_pk_mul_f32 v[52:53], v[62:63], v[50:51] op_sel_hi:[1,0]
	v_pk_fma_f32 v[2:3], v[4:5], v[200:201], v[216:217]
	global_store_dwordx4 v[48:49], v[0:3], off offset:1024
	s_nop 1
	v_cndmask_b32_e32 v19, v46, v19, vcc
	v_rsq_f32_e32 v19, v19
	v_pk_fma_f32 v[0:1], v[52:53], v[202:203], v[218:219]
	v_pk_mul_f32 v[4:5], v[58:59], v[50:51] op_sel_hi:[1,0]
	v_mul_f32_e32 v21, 0x45800000, v19
	v_pk_fma_f32 v[2:3], v[4:5], v[204:205], v[220:221]
	global_store_dwordx4 v[48:49], v[0:3], off offset:2048
	s_nop 1
	v_pk_fma_f32 v[0:1], v[42:43], v[206:207], v[222:223]
	v_pk_fma_f32 v[2:3], v[40:41], v[208:209], v[224:225]
	global_store_dwordx4 v[48:49], v[0:3], off offset:3072
	s_nop 1
	v_cndmask_b32_e32 v40, v19, v21, vcc
	v_pk_mul_f32 v[42:43], v[44:45], v[40:41] op_sel_hi:[1,0]
	v_pk_mul_f32 v[38:39], v[38:39], v[40:41] op_sel_hi:[1,0]
	v_pk_mul_f32 v[36:37], v[36:37], v[40:41] op_sel_hi:[1,0]
	v_pk_mul_f32 v[34:35], v[34:35], v[40:41] op_sel_hi:[1,0]
	v_pk_mul_f32 v[32:33], v[32:33], v[40:41] op_sel_hi:[1,0]
	v_pk_mul_f32 v[30:31], v[30:31], v[40:41] op_sel_hi:[1,0]
	v_cmp_lt_i32_e32 vcc, s9, v23
	v_pk_mul_f32 v[28:29], v[28:29], v[40:41] op_sel_hi:[1,0]
	v_pk_mul_f32 v[26:27], v[26:27], v[40:41] op_sel_hi:[1,0]
	s_or_b64 s[0:1], vcc, s[0:1]
	v_pk_fma_f32 v[0:1], v[194:195], v[42:43], v[210:211]
	v_pk_fma_f32 v[2:3], v[196:197], v[38:39], v[212:213]
	global_store_dwordx4 v[24:25], v[0:3], off
	s_nop 1
	v_pk_fma_f32 v[0:1], v[36:37], v[198:199], v[214:215]
	v_pk_fma_f32 v[2:3], v[34:35], v[200:201], v[216:217]
	global_store_dwordx4 v[24:25], v[0:3], off offset:1024
	s_nop 1
	v_pk_fma_f32 v[0:1], v[32:33], v[202:203], v[218:219]
	v_pk_fma_f32 v[2:3], v[30:31], v[204:205], v[220:221]
	global_store_dwordx4 v[24:25], v[0:3], off offset:2048
	s_nop 1
	v_pk_fma_f32 v[0:1], v[28:29], v[206:207], v[222:223]
	v_pk_fma_f32 v[2:3], v[26:27], v[208:209], v[224:225]
	global_store_dwordx4 v[24:25], v[0:3], off offset:3072
	s_nop 1
	s_andn2_b64 exec, exec, s[0:1]
	s_cbranch_execnz .LBB0_1430
